# phases 0 and 5 norm loops also replaced by the hand-written 3-deep pipelined loop (x nt); phase 9 as before
# speedup vs baseline: 1.0328x; 1.0022x over previous
.LBB0_98:
	s_or_b64 exec, exec, s[8:9]
	s_mov_b32 s7, 0x8000
	v_cmp_gt_i32_e32 vcc, s7, v38
	v_lshlrev_b32_e32 v40, 4, v45
	s_and_saveexec_b64 s[4:5], vcc
	s_cbranch_execz .LBB0_111
	s_waitcnt vmcnt(0) lgkmcnt(0)
	v_readfirstlane_b32 s13, v209
	s_lshl_b32 s14, s96, 3
	s_add_u32 s14, s14, s13
	s_lshl_b32 s15, s82, 3
	s_cmp_ge_u32 s14, 0x8000
	s_cbranch_scc1 .LBB0_111
	v_and_b32_e32 v190, 63, v208
	v_lshlrev_b32_e32 v191, 3, v190
	v_lshlrev_b32_e32 v190, 4, v190
	global_load_dwordx4 v[160:163], v190, s[40:41] offset:0
	global_load_dwordx4 v[164:167], v190, s[40:41] offset:1024
	global_load_dwordx4 v[168:171], v190, s[40:41] offset:2048
	global_load_dwordx4 v[172:175], v190, s[40:41] offset:3072
	v_mov_b32_e32 v188, 0x3a800000
	v_mov_b32_e32 v189, 0x358637bd
	s_lshl_b32 s13, s14, 12
	s_add_u32 s0, s36, s13
	s_addc_u32 s1, s37, 0
	s_lshl_b32 s13, s14, 11
	s_add_u32 s8, s20, s13
	s_addc_u32 s9, s21, 0
	s_add_u32 s8, s8, 0xf60000
	s_addc_u32 s9, s9, 0
	s_lshl_b32 s10, s15, 12
	s_lshl_b32 s12, s15, 11
	global_load_dwordx4 v[64:67], v190, s[0:1] nt
	global_load_dwordx4 v[68:71], v190, s[0:1] offset:1024 nt
	global_load_dwordx4 v[72:75], v190, s[0:1] offset:2048 nt
	global_load_dwordx4 v[76:79], v190, s[0:1] offset:3072 nt
	s_add_u32 s0, s0, s10
	s_addc_u32 s1, s1, 0
	s_add_u32 s14, s14, s15
	s_cmp_ge_u32 s14, 0x8000
	s_cbranch_scc0 .Lpnorm_two
	s_waitcnt vmcnt(0)
	v_pk_mul_f32 v[184:185], v[64:65], v[64:65]
	v_pk_mul_f32 v[176:177], v[66:67], v[66:67]
	v_pk_fma_f32 v[184:185], v[68:69], v[68:69], v[184:185]
	v_pk_fma_f32 v[176:177], v[70:71], v[70:71], v[176:177]
	v_pk_fma_f32 v[184:185], v[72:73], v[72:73], v[184:185]
	v_pk_fma_f32 v[176:177], v[74:75], v[74:75], v[176:177]
	v_pk_fma_f32 v[184:185], v[76:77], v[76:77], v[184:185]
	v_pk_fma_f32 v[176:177], v[78:79], v[78:79], v[176:177]
	v_pk_add_f32 v[184:185], v[184:185], v[176:177]
	s_nop 0
	v_add_f32_e32 v184, v184, v185
	s_nop 1
	v_add_f32_dpp v184, v184, v184 quad_perm:[1,0,3,2] row_mask:0xf bank_mask:0xf
	s_nop 1
	v_add_f32_dpp v184, v184, v184 quad_perm:[2,3,0,1] row_mask:0xf bank_mask:0xf
	s_nop 1
	v_add_f32_dpp v184, v184, v184 row_half_mirror row_mask:0xf bank_mask:0xf
	s_nop 1
	v_add_f32_dpp v184, v184, v184 row_mirror row_mask:0xf bank_mask:0xf
	s_nop 1
	v_add_f32_dpp v184, v184, v184 row_bcast:15 row_mask:0xa bank_mask:0xf
	s_nop 1
	v_add_f32_dpp v184, v184, v184 row_bcast:31 row_mask:0xc bank_mask:0xf
	s_nop 1
	v_readlane_b32 s13, v184, 63
	s_nop 3
	v_fma_f32 v186, s13, v188, v189
	v_rsq_f32_e32 v186, v186
	s_nop 0
	v_mov_b32_e32 v187, v186
	v_pk_mul_f32 v[64:65], v[64:65], v[186:187]
	v_pk_mul_f32 v[66:67], v[66:67], v[186:187]
	v_pk_mul_f32 v[68:69], v[68:69], v[186:187]
	v_pk_mul_f32 v[70:71], v[70:71], v[186:187]
	v_pk_mul_f32 v[72:73], v[72:73], v[186:187]
	v_pk_mul_f32 v[74:75], v[74:75], v[186:187]
	v_pk_mul_f32 v[76:77], v[76:77], v[186:187]
	v_pk_mul_f32 v[78:79], v[78:79], v[186:187]
	v_pk_mul_f32 v[64:65], v[64:65], v[160:161]
	v_pk_mul_f32 v[66:67], v[66:67], v[162:163]
	v_pk_mul_f32 v[68:69], v[68:69], v[164:165]
	v_pk_mul_f32 v[70:71], v[70:71], v[166:167]
	v_pk_mul_f32 v[72:73], v[72:73], v[168:169]
	v_pk_mul_f32 v[74:75], v[74:75], v[170:171]
	v_pk_mul_f32 v[76:77], v[76:77], v[172:173]
	v_pk_mul_f32 v[78:79], v[78:79], v[174:175]
	v_cvt_pk_bf16_f32 v176, v64, v65
	v_cvt_pk_bf16_f32 v177, v66, v67
	v_cvt_pk_bf16_f32 v178, v68, v69
	v_cvt_pk_bf16_f32 v179, v70, v71
	v_cvt_pk_bf16_f32 v180, v72, v73
	v_cvt_pk_bf16_f32 v181, v74, v75
	v_cvt_pk_bf16_f32 v182, v76, v77
	v_cvt_pk_bf16_f32 v183, v78, v79
	global_store_dwordx2 v191, v[176:177], s[8:9]
	global_store_dwordx2 v191, v[178:179], s[8:9] offset:512
	global_store_dwordx2 v191, v[180:181], s[8:9] offset:1024
	global_store_dwordx2 v191, v[182:183], s[8:9] offset:1536
	s_add_u32 s8, s8, s12
	s_addc_u32 s9, s9, 0
	s_branch .Lpnorm_done
.Lpnorm_two:
	global_load_dwordx4 v[96:99], v190, s[0:1] nt
	global_load_dwordx4 v[100:103], v190, s[0:1] offset:1024 nt
	global_load_dwordx4 v[104:107], v190, s[0:1] offset:2048 nt
	global_load_dwordx4 v[108:111], v190, s[0:1] offset:3072 nt
	s_add_u32 s0, s0, s10
	s_addc_u32 s1, s1, 0
	s_add_u32 s14, s14, s15
.Lpnorm_loop:
	s_cmp_ge_u32 s14, 0x8000
	s_cbranch_scc1 .Lpnorm_drain0
	global_load_dwordx4 v[128:131], v190, s[0:1] nt
	global_load_dwordx4 v[132:135], v190, s[0:1] offset:1024 nt
	global_load_dwordx4 v[136:139], v190, s[0:1] offset:2048 nt
	global_load_dwordx4 v[140:143], v190, s[0:1] offset:3072 nt
	s_add_u32 s0, s0, s10
	s_addc_u32 s1, s1, 0
	s_add_u32 s14, s14, s15
	s_waitcnt vmcnt(8)
	v_pk_mul_f32 v[184:185], v[64:65], v[64:65]
	v_pk_mul_f32 v[176:177], v[66:67], v[66:67]
	v_pk_fma_f32 v[184:185], v[68:69], v[68:69], v[184:185]
	v_pk_fma_f32 v[176:177], v[70:71], v[70:71], v[176:177]
	v_pk_fma_f32 v[184:185], v[72:73], v[72:73], v[184:185]
	v_pk_fma_f32 v[176:177], v[74:75], v[74:75], v[176:177]
	v_pk_fma_f32 v[184:185], v[76:77], v[76:77], v[184:185]
	v_pk_fma_f32 v[176:177], v[78:79], v[78:79], v[176:177]
	v_pk_add_f32 v[184:185], v[184:185], v[176:177]
	s_nop 0
	v_add_f32_e32 v184, v184, v185
	s_nop 1
	v_add_f32_dpp v184, v184, v184 quad_perm:[1,0,3,2] row_mask:0xf bank_mask:0xf
	s_nop 1
	v_add_f32_dpp v184, v184, v184 quad_perm:[2,3,0,1] row_mask:0xf bank_mask:0xf
	s_nop 1
	v_add_f32_dpp v184, v184, v184 row_half_mirror row_mask:0xf bank_mask:0xf
	s_nop 1
	v_add_f32_dpp v184, v184, v184 row_mirror row_mask:0xf bank_mask:0xf
	s_nop 1
	v_add_f32_dpp v184, v184, v184 row_bcast:15 row_mask:0xa bank_mask:0xf
	s_nop 1
	v_add_f32_dpp v184, v184, v184 row_bcast:31 row_mask:0xc bank_mask:0xf
	s_nop 1
	v_readlane_b32 s13, v184, 63
	s_nop 3
	v_fma_f32 v186, s13, v188, v189
	v_rsq_f32_e32 v186, v186
	s_nop 0
	v_mov_b32_e32 v187, v186
	v_pk_mul_f32 v[64:65], v[64:65], v[186:187]
	v_pk_mul_f32 v[66:67], v[66:67], v[186:187]
	v_pk_mul_f32 v[68:69], v[68:69], v[186:187]
	v_pk_mul_f32 v[70:71], v[70:71], v[186:187]
	v_pk_mul_f32 v[72:73], v[72:73], v[186:187]
	v_pk_mul_f32 v[74:75], v[74:75], v[186:187]
	v_pk_mul_f32 v[76:77], v[76:77], v[186:187]
	v_pk_mul_f32 v[78:79], v[78:79], v[186:187]
	v_pk_mul_f32 v[64:65], v[64:65], v[160:161]
	v_pk_mul_f32 v[66:67], v[66:67], v[162:163]
	v_pk_mul_f32 v[68:69], v[68:69], v[164:165]
	v_pk_mul_f32 v[70:71], v[70:71], v[166:167]
	v_pk_mul_f32 v[72:73], v[72:73], v[168:169]
	v_pk_mul_f32 v[74:75], v[74:75], v[170:171]
	v_pk_mul_f32 v[76:77], v[76:77], v[172:173]
	v_pk_mul_f32 v[78:79], v[78:79], v[174:175]
	v_cvt_pk_bf16_f32 v176, v64, v65
	v_cvt_pk_bf16_f32 v177, v66, v67
	v_cvt_pk_bf16_f32 v178, v68, v69
	v_cvt_pk_bf16_f32 v179, v70, v71
	v_cvt_pk_bf16_f32 v180, v72, v73
	v_cvt_pk_bf16_f32 v181, v74, v75
	v_cvt_pk_bf16_f32 v182, v76, v77
	v_cvt_pk_bf16_f32 v183, v78, v79
	global_store_dwordx2 v191, v[176:177], s[8:9]
	global_store_dwordx2 v191, v[178:179], s[8:9] offset:512
	global_store_dwordx2 v191, v[180:181], s[8:9] offset:1024
	global_store_dwordx2 v191, v[182:183], s[8:9] offset:1536
	s_add_u32 s8, s8, s12
	s_addc_u32 s9, s9, 0
	s_cmp_ge_u32 s14, 0x8000
	s_cbranch_scc1 .Lpnorm_drain1
	global_load_dwordx4 v[64:67], v190, s[0:1] nt
	global_load_dwordx4 v[68:71], v190, s[0:1] offset:1024 nt
	global_load_dwordx4 v[72:75], v190, s[0:1] offset:2048 nt
	global_load_dwordx4 v[76:79], v190, s[0:1] offset:3072 nt
	s_add_u32 s0, s0, s10
	s_addc_u32 s1, s1, 0
	s_add_u32 s14, s14, s15
	s_waitcnt vmcnt(8)
	v_pk_mul_f32 v[184:185], v[96:97], v[96:97]
	v_pk_mul_f32 v[176:177], v[98:99], v[98:99]
	v_pk_fma_f32 v[184:185], v[100:101], v[100:101], v[184:185]
	v_pk_fma_f32 v[176:177], v[102:103], v[102:103], v[176:177]
	v_pk_fma_f32 v[184:185], v[104:105], v[104:105], v[184:185]
	v_pk_fma_f32 v[176:177], v[106:107], v[106:107], v[176:177]
	v_pk_fma_f32 v[184:185], v[108:109], v[108:109], v[184:185]
	v_pk_fma_f32 v[176:177], v[110:111], v[110:111], v[176:177]
	v_pk_add_f32 v[184:185], v[184:185], v[176:177]
	s_nop 0
	v_add_f32_e32 v184, v184, v185
	s_nop 1
	v_add_f32_dpp v184, v184, v184 quad_perm:[1,0,3,2] row_mask:0xf bank_mask:0xf
	s_nop 1
	v_add_f32_dpp v184, v184, v184 quad_perm:[2,3,0,1] row_mask:0xf bank_mask:0xf
	s_nop 1
	v_add_f32_dpp v184, v184, v184 row_half_mirror row_mask:0xf bank_mask:0xf
	s_nop 1
	v_add_f32_dpp v184, v184, v184 row_mirror row_mask:0xf bank_mask:0xf
	s_nop 1
	v_add_f32_dpp v184, v184, v184 row_bcast:15 row_mask:0xa bank_mask:0xf
	s_nop 1
	v_add_f32_dpp v184, v184, v184 row_bcast:31 row_mask:0xc bank_mask:0xf
	s_nop 1
	v_readlane_b32 s13, v184, 63
	s_nop 3
	v_fma_f32 v186, s13, v188, v189
	v_rsq_f32_e32 v186, v186
	s_nop 0
	v_mov_b32_e32 v187, v186
	v_pk_mul_f32 v[96:97], v[96:97], v[186:187]
	v_pk_mul_f32 v[98:99], v[98:99], v[186:187]
	v_pk_mul_f32 v[100:101], v[100:101], v[186:187]
	v_pk_mul_f32 v[102:103], v[102:103], v[186:187]
	v_pk_mul_f32 v[104:105], v[104:105], v[186:187]
	v_pk_mul_f32 v[106:107], v[106:107], v[186:187]
	v_pk_mul_f32 v[108:109], v[108:109], v[186:187]
	v_pk_mul_f32 v[110:111], v[110:111], v[186:187]
	v_pk_mul_f32 v[96:97], v[96:97], v[160:161]
	v_pk_mul_f32 v[98:99], v[98:99], v[162:163]
	v_pk_mul_f32 v[100:101], v[100:101], v[164:165]
	v_pk_mul_f32 v[102:103], v[102:103], v[166:167]
	v_pk_mul_f32 v[104:105], v[104:105], v[168:169]
	v_pk_mul_f32 v[106:107], v[106:107], v[170:171]
	v_pk_mul_f32 v[108:109], v[108:109], v[172:173]
	v_pk_mul_f32 v[110:111], v[110:111], v[174:175]
	v_cvt_pk_bf16_f32 v176, v96, v97
	v_cvt_pk_bf16_f32 v177, v98, v99
	v_cvt_pk_bf16_f32 v178, v100, v101
	v_cvt_pk_bf16_f32 v179, v102, v103
	v_cvt_pk_bf16_f32 v180, v104, v105
	v_cvt_pk_bf16_f32 v181, v106, v107
	v_cvt_pk_bf16_f32 v182, v108, v109
	v_cvt_pk_bf16_f32 v183, v110, v111
	global_store_dwordx2 v191, v[176:177], s[8:9]
	global_store_dwordx2 v191, v[178:179], s[8:9] offset:512
	global_store_dwordx2 v191, v[180:181], s[8:9] offset:1024
	global_store_dwordx2 v191, v[182:183], s[8:9] offset:1536
	s_add_u32 s8, s8, s12
	s_addc_u32 s9, s9, 0
	s_cmp_ge_u32 s14, 0x8000
	s_cbranch_scc1 .Lpnorm_drain2
	global_load_dwordx4 v[96:99], v190, s[0:1] nt
	global_load_dwordx4 v[100:103], v190, s[0:1] offset:1024 nt
	global_load_dwordx4 v[104:107], v190, s[0:1] offset:2048 nt
	global_load_dwordx4 v[108:111], v190, s[0:1] offset:3072 nt
	s_add_u32 s0, s0, s10
	s_addc_u32 s1, s1, 0
	s_add_u32 s14, s14, s15
	s_waitcnt vmcnt(8)
	v_pk_mul_f32 v[184:185], v[128:129], v[128:129]
	v_pk_mul_f32 v[176:177], v[130:131], v[130:131]
	v_pk_fma_f32 v[184:185], v[132:133], v[132:133], v[184:185]
	v_pk_fma_f32 v[176:177], v[134:135], v[134:135], v[176:177]
	v_pk_fma_f32 v[184:185], v[136:137], v[136:137], v[184:185]
	v_pk_fma_f32 v[176:177], v[138:139], v[138:139], v[176:177]
	v_pk_fma_f32 v[184:185], v[140:141], v[140:141], v[184:185]
	v_pk_fma_f32 v[176:177], v[142:143], v[142:143], v[176:177]
	v_pk_add_f32 v[184:185], v[184:185], v[176:177]
	s_nop 0
	v_add_f32_e32 v184, v184, v185
	s_nop 1
	v_add_f32_dpp v184, v184, v184 quad_perm:[1,0,3,2] row_mask:0xf bank_mask:0xf
	s_nop 1
	v_add_f32_dpp v184, v184, v184 quad_perm:[2,3,0,1] row_mask:0xf bank_mask:0xf
	s_nop 1
	v_add_f32_dpp v184, v184, v184 row_half_mirror row_mask:0xf bank_mask:0xf
	s_nop 1
	v_add_f32_dpp v184, v184, v184 row_mirror row_mask:0xf bank_mask:0xf
	s_nop 1
	v_add_f32_dpp v184, v184, v184 row_bcast:15 row_mask:0xa bank_mask:0xf
	s_nop 1
	v_add_f32_dpp v184, v184, v184 row_bcast:31 row_mask:0xc bank_mask:0xf
	s_nop 1
	v_readlane_b32 s13, v184, 63
	s_nop 3
	v_fma_f32 v186, s13, v188, v189
	v_rsq_f32_e32 v186, v186
	s_nop 0
	v_mov_b32_e32 v187, v186
	v_pk_mul_f32 v[128:129], v[128:129], v[186:187]
	v_pk_mul_f32 v[130:131], v[130:131], v[186:187]
	v_pk_mul_f32 v[132:133], v[132:133], v[186:187]
	v_pk_mul_f32 v[134:135], v[134:135], v[186:187]
	v_pk_mul_f32 v[136:137], v[136:137], v[186:187]
	v_pk_mul_f32 v[138:139], v[138:139], v[186:187]
	v_pk_mul_f32 v[140:141], v[140:141], v[186:187]
	v_pk_mul_f32 v[142:143], v[142:143], v[186:187]
	v_pk_mul_f32 v[128:129], v[128:129], v[160:161]
	v_pk_mul_f32 v[130:131], v[130:131], v[162:163]
	v_pk_mul_f32 v[132:133], v[132:133], v[164:165]
	v_pk_mul_f32 v[134:135], v[134:135], v[166:167]
	v_pk_mul_f32 v[136:137], v[136:137], v[168:169]
	v_pk_mul_f32 v[138:139], v[138:139], v[170:171]
	v_pk_mul_f32 v[140:141], v[140:141], v[172:173]
	v_pk_mul_f32 v[142:143], v[142:143], v[174:175]
	v_cvt_pk_bf16_f32 v176, v128, v129
	v_cvt_pk_bf16_f32 v177, v130, v131
	v_cvt_pk_bf16_f32 v178, v132, v133
	v_cvt_pk_bf16_f32 v179, v134, v135
	v_cvt_pk_bf16_f32 v180, v136, v137
	v_cvt_pk_bf16_f32 v181, v138, v139
	v_cvt_pk_bf16_f32 v182, v140, v141
	v_cvt_pk_bf16_f32 v183, v142, v143
	global_store_dwordx2 v191, v[176:177], s[8:9]
	global_store_dwordx2 v191, v[178:179], s[8:9] offset:512
	global_store_dwordx2 v191, v[180:181], s[8:9] offset:1024
	global_store_dwordx2 v191, v[182:183], s[8:9] offset:1536
	s_add_u32 s8, s8, s12
	s_addc_u32 s9, s9, 0
	s_branch .Lpnorm_loop
.Lpnorm_drain0:
	s_waitcnt vmcnt(4)
	v_pk_mul_f32 v[184:185], v[64:65], v[64:65]
	v_pk_mul_f32 v[176:177], v[66:67], v[66:67]
	v_pk_fma_f32 v[184:185], v[68:69], v[68:69], v[184:185]
	v_pk_fma_f32 v[176:177], v[70:71], v[70:71], v[176:177]
	v_pk_fma_f32 v[184:185], v[72:73], v[72:73], v[184:185]
	v_pk_fma_f32 v[176:177], v[74:75], v[74:75], v[176:177]
	v_pk_fma_f32 v[184:185], v[76:77], v[76:77], v[184:185]
	v_pk_fma_f32 v[176:177], v[78:79], v[78:79], v[176:177]
	v_pk_add_f32 v[184:185], v[184:185], v[176:177]
	s_nop 0
	v_add_f32_e32 v184, v184, v185
	s_nop 1
	v_add_f32_dpp v184, v184, v184 quad_perm:[1,0,3,2] row_mask:0xf bank_mask:0xf
	s_nop 1
	v_add_f32_dpp v184, v184, v184 quad_perm:[2,3,0,1] row_mask:0xf bank_mask:0xf
	s_nop 1
	v_add_f32_dpp v184, v184, v184 row_half_mirror row_mask:0xf bank_mask:0xf
	s_nop 1
	v_add_f32_dpp v184, v184, v184 row_mirror row_mask:0xf bank_mask:0xf
	s_nop 1
	v_add_f32_dpp v184, v184, v184 row_bcast:15 row_mask:0xa bank_mask:0xf
	s_nop 1
	v_add_f32_dpp v184, v184, v184 row_bcast:31 row_mask:0xc bank_mask:0xf
	s_nop 1
	v_readlane_b32 s13, v184, 63
	s_nop 3
	v_fma_f32 v186, s13, v188, v189
	v_rsq_f32_e32 v186, v186
	s_nop 0
	v_mov_b32_e32 v187, v186
	v_pk_mul_f32 v[64:65], v[64:65], v[186:187]
	v_pk_mul_f32 v[66:67], v[66:67], v[186:187]
	v_pk_mul_f32 v[68:69], v[68:69], v[186:187]
	v_pk_mul_f32 v[70:71], v[70:71], v[186:187]
	v_pk_mul_f32 v[72:73], v[72:73], v[186:187]
	v_pk_mul_f32 v[74:75], v[74:75], v[186:187]
	v_pk_mul_f32 v[76:77], v[76:77], v[186:187]
	v_pk_mul_f32 v[78:79], v[78:79], v[186:187]
	v_pk_mul_f32 v[64:65], v[64:65], v[160:161]
	v_pk_mul_f32 v[66:67], v[66:67], v[162:163]
	v_pk_mul_f32 v[68:69], v[68:69], v[164:165]
	v_pk_mul_f32 v[70:71], v[70:71], v[166:167]
	v_pk_mul_f32 v[72:73], v[72:73], v[168:169]
	v_pk_mul_f32 v[74:75], v[74:75], v[170:171]
	v_pk_mul_f32 v[76:77], v[76:77], v[172:173]
	v_pk_mul_f32 v[78:79], v[78:79], v[174:175]
	v_cvt_pk_bf16_f32 v176, v64, v65
	v_cvt_pk_bf16_f32 v177, v66, v67
	v_cvt_pk_bf16_f32 v178, v68, v69
	v_cvt_pk_bf16_f32 v179, v70, v71
	v_cvt_pk_bf16_f32 v180, v72, v73
	v_cvt_pk_bf16_f32 v181, v74, v75
	v_cvt_pk_bf16_f32 v182, v76, v77
	v_cvt_pk_bf16_f32 v183, v78, v79
	global_store_dwordx2 v191, v[176:177], s[8:9]
	global_store_dwordx2 v191, v[178:179], s[8:9] offset:512
	global_store_dwordx2 v191, v[180:181], s[8:9] offset:1024
	global_store_dwordx2 v191, v[182:183], s[8:9] offset:1536
	s_add_u32 s8, s8, s12
	s_addc_u32 s9, s9, 0
	s_waitcnt vmcnt(4)
	v_pk_mul_f32 v[184:185], v[96:97], v[96:97]
	v_pk_mul_f32 v[176:177], v[98:99], v[98:99]
	v_pk_fma_f32 v[184:185], v[100:101], v[100:101], v[184:185]
	v_pk_fma_f32 v[176:177], v[102:103], v[102:103], v[176:177]
	v_pk_fma_f32 v[184:185], v[104:105], v[104:105], v[184:185]
	v_pk_fma_f32 v[176:177], v[106:107], v[106:107], v[176:177]
	v_pk_fma_f32 v[184:185], v[108:109], v[108:109], v[184:185]
	v_pk_fma_f32 v[176:177], v[110:111], v[110:111], v[176:177]
	v_pk_add_f32 v[184:185], v[184:185], v[176:177]
	s_nop 0
	v_add_f32_e32 v184, v184, v185
	s_nop 1
	v_add_f32_dpp v184, v184, v184 quad_perm:[1,0,3,2] row_mask:0xf bank_mask:0xf
	s_nop 1
	v_add_f32_dpp v184, v184, v184 quad_perm:[2,3,0,1] row_mask:0xf bank_mask:0xf
	s_nop 1
	v_add_f32_dpp v184, v184, v184 row_half_mirror row_mask:0xf bank_mask:0xf
	s_nop 1
	v_add_f32_dpp v184, v184, v184 row_mirror row_mask:0xf bank_mask:0xf
	s_nop 1
	v_add_f32_dpp v184, v184, v184 row_bcast:15 row_mask:0xa bank_mask:0xf
	s_nop 1
	v_add_f32_dpp v184, v184, v184 row_bcast:31 row_mask:0xc bank_mask:0xf
	s_nop 1
	v_readlane_b32 s13, v184, 63
	s_nop 3
	v_fma_f32 v186, s13, v188, v189
	v_rsq_f32_e32 v186, v186
	s_nop 0
	v_mov_b32_e32 v187, v186
	v_pk_mul_f32 v[96:97], v[96:97], v[186:187]
	v_pk_mul_f32 v[98:99], v[98:99], v[186:187]
	v_pk_mul_f32 v[100:101], v[100:101], v[186:187]
	v_pk_mul_f32 v[102:103], v[102:103], v[186:187]
	v_pk_mul_f32 v[104:105], v[104:105], v[186:187]
	v_pk_mul_f32 v[106:107], v[106:107], v[186:187]
	v_pk_mul_f32 v[108:109], v[108:109], v[186:187]
	v_pk_mul_f32 v[110:111], v[110:111], v[186:187]
	v_pk_mul_f32 v[96:97], v[96:97], v[160:161]
	v_pk_mul_f32 v[98:99], v[98:99], v[162:163]
	v_pk_mul_f32 v[100:101], v[100:101], v[164:165]
	v_pk_mul_f32 v[102:103], v[102:103], v[166:167]
	v_pk_mul_f32 v[104:105], v[104:105], v[168:169]
	v_pk_mul_f32 v[106:107], v[106:107], v[170:171]
	v_pk_mul_f32 v[108:109], v[108:109], v[172:173]
	v_pk_mul_f32 v[110:111], v[110:111], v[174:175]
	v_cvt_pk_bf16_f32 v176, v96, v97
	v_cvt_pk_bf16_f32 v177, v98, v99
	v_cvt_pk_bf16_f32 v178, v100, v101
	v_cvt_pk_bf16_f32 v179, v102, v103
	v_cvt_pk_bf16_f32 v180, v104, v105
	v_cvt_pk_bf16_f32 v181, v106, v107
	v_cvt_pk_bf16_f32 v182, v108, v109
	v_cvt_pk_bf16_f32 v183, v110, v111
	global_store_dwordx2 v191, v[176:177], s[8:9]
	global_store_dwordx2 v191, v[178:179], s[8:9] offset:512
	global_store_dwordx2 v191, v[180:181], s[8:9] offset:1024
	global_store_dwordx2 v191, v[182:183], s[8:9] offset:1536
	s_add_u32 s8, s8, s12
	s_addc_u32 s9, s9, 0
	s_branch .Lpnorm_done
.Lpnorm_drain1:
	s_waitcnt vmcnt(4)
	v_pk_mul_f32 v[184:185], v[96:97], v[96:97]
	v_pk_mul_f32 v[176:177], v[98:99], v[98:99]
	v_pk_fma_f32 v[184:185], v[100:101], v[100:101], v[184:185]
	v_pk_fma_f32 v[176:177], v[102:103], v[102:103], v[176:177]
	v_pk_fma_f32 v[184:185], v[104:105], v[104:105], v[184:185]
	v_pk_fma_f32 v[176:177], v[106:107], v[106:107], v[176:177]
	v_pk_fma_f32 v[184:185], v[108:109], v[108:109], v[184:185]
	v_pk_fma_f32 v[176:177], v[110:111], v[110:111], v[176:177]
	v_pk_add_f32 v[184:185], v[184:185], v[176:177]
	s_nop 0
	v_add_f32_e32 v184, v184, v185
	s_nop 1
	v_add_f32_dpp v184, v184, v184 quad_perm:[1,0,3,2] row_mask:0xf bank_mask:0xf
	s_nop 1
	v_add_f32_dpp v184, v184, v184 quad_perm:[2,3,0,1] row_mask:0xf bank_mask:0xf
	s_nop 1
	v_add_f32_dpp v184, v184, v184 row_half_mirror row_mask:0xf bank_mask:0xf
	s_nop 1
	v_add_f32_dpp v184, v184, v184 row_mirror row_mask:0xf bank_mask:0xf
	s_nop 1
	v_add_f32_dpp v184, v184, v184 row_bcast:15 row_mask:0xa bank_mask:0xf
	s_nop 1
	v_add_f32_dpp v184, v184, v184 row_bcast:31 row_mask:0xc bank_mask:0xf
	s_nop 1
	v_readlane_b32 s13, v184, 63
	s_nop 3
	v_fma_f32 v186, s13, v188, v189
	v_rsq_f32_e32 v186, v186
	s_nop 0
	v_mov_b32_e32 v187, v186
	v_pk_mul_f32 v[96:97], v[96:97], v[186:187]
	v_pk_mul_f32 v[98:99], v[98:99], v[186:187]
	v_pk_mul_f32 v[100:101], v[100:101], v[186:187]
	v_pk_mul_f32 v[102:103], v[102:103], v[186:187]
	v_pk_mul_f32 v[104:105], v[104:105], v[186:187]
	v_pk_mul_f32 v[106:107], v[106:107], v[186:187]
	v_pk_mul_f32 v[108:109], v[108:109], v[186:187]
	v_pk_mul_f32 v[110:111], v[110:111], v[186:187]
	v_pk_mul_f32 v[96:97], v[96:97], v[160:161]
	v_pk_mul_f32 v[98:99], v[98:99], v[162:163]
	v_pk_mul_f32 v[100:101], v[100:101], v[164:165]
	v_pk_mul_f32 v[102:103], v[102:103], v[166:167]
	v_pk_mul_f32 v[104:105], v[104:105], v[168:169]
	v_pk_mul_f32 v[106:107], v[106:107], v[170:171]
	v_pk_mul_f32 v[108:109], v[108:109], v[172:173]
	v_pk_mul_f32 v[110:111], v[110:111], v[174:175]
	v_cvt_pk_bf16_f32 v176, v96, v97
	v_cvt_pk_bf16_f32 v177, v98, v99
	v_cvt_pk_bf16_f32 v178, v100, v101
	v_cvt_pk_bf16_f32 v179, v102, v103
	v_cvt_pk_bf16_f32 v180, v104, v105
	v_cvt_pk_bf16_f32 v181, v106, v107
	v_cvt_pk_bf16_f32 v182, v108, v109
	v_cvt_pk_bf16_f32 v183, v110, v111
	global_store_dwordx2 v191, v[176:177], s[8:9]
	global_store_dwordx2 v191, v[178:179], s[8:9] offset:512
	global_store_dwordx2 v191, v[180:181], s[8:9] offset:1024
	global_store_dwordx2 v191, v[182:183], s[8:9] offset:1536
	s_add_u32 s8, s8, s12
	s_addc_u32 s9, s9, 0
	s_waitcnt vmcnt(4)
	v_pk_mul_f32 v[184:185], v[128:129], v[128:129]
	v_pk_mul_f32 v[176:177], v[130:131], v[130:131]
	v_pk_fma_f32 v[184:185], v[132:133], v[132:133], v[184:185]
	v_pk_fma_f32 v[176:177], v[134:135], v[134:135], v[176:177]
	v_pk_fma_f32 v[184:185], v[136:137], v[136:137], v[184:185]
	v_pk_fma_f32 v[176:177], v[138:139], v[138:139], v[176:177]
	v_pk_fma_f32 v[184:185], v[140:141], v[140:141], v[184:185]
	v_pk_fma_f32 v[176:177], v[142:143], v[142:143], v[176:177]
	v_pk_add_f32 v[184:185], v[184:185], v[176:177]
	s_nop 0
	v_add_f32_e32 v184, v184, v185
	s_nop 1
	v_add_f32_dpp v184, v184, v184 quad_perm:[1,0,3,2] row_mask:0xf bank_mask:0xf
	s_nop 1
	v_add_f32_dpp v184, v184, v184 quad_perm:[2,3,0,1] row_mask:0xf bank_mask:0xf
	s_nop 1
	v_add_f32_dpp v184, v184, v184 row_half_mirror row_mask:0xf bank_mask:0xf
	s_nop 1
	v_add_f32_dpp v184, v184, v184 row_mirror row_mask:0xf bank_mask:0xf
	s_nop 1
	v_add_f32_dpp v184, v184, v184 row_bcast:15 row_mask:0xa bank_mask:0xf
	s_nop 1
	v_add_f32_dpp v184, v184, v184 row_bcast:31 row_mask:0xc bank_mask:0xf
	s_nop 1
	v_readlane_b32 s13, v184, 63
	s_nop 3
	v_fma_f32 v186, s13, v188, v189
	v_rsq_f32_e32 v186, v186
	s_nop 0
	v_mov_b32_e32 v187, v186
	v_pk_mul_f32 v[128:129], v[128:129], v[186:187]
	v_pk_mul_f32 v[130:131], v[130:131], v[186:187]
	v_pk_mul_f32 v[132:133], v[132:133], v[186:187]
	v_pk_mul_f32 v[134:135], v[134:135], v[186:187]
	v_pk_mul_f32 v[136:137], v[136:137], v[186:187]
	v_pk_mul_f32 v[138:139], v[138:139], v[186:187]
	v_pk_mul_f32 v[140:141], v[140:141], v[186:187]
	v_pk_mul_f32 v[142:143], v[142:143], v[186:187]
	v_pk_mul_f32 v[128:129], v[128:129], v[160:161]
	v_pk_mul_f32 v[130:131], v[130:131], v[162:163]
	v_pk_mul_f32 v[132:133], v[132:133], v[164:165]
	v_pk_mul_f32 v[134:135], v[134:135], v[166:167]
	v_pk_mul_f32 v[136:137], v[136:137], v[168:169]
	v_pk_mul_f32 v[138:139], v[138:139], v[170:171]
	v_pk_mul_f32 v[140:141], v[140:141], v[172:173]
	v_pk_mul_f32 v[142:143], v[142:143], v[174:175]
	v_cvt_pk_bf16_f32 v176, v128, v129
	v_cvt_pk_bf16_f32 v177, v130, v131
	v_cvt_pk_bf16_f32 v178, v132, v133
	v_cvt_pk_bf16_f32 v179, v134, v135
	v_cvt_pk_bf16_f32 v180, v136, v137
	v_cvt_pk_bf16_f32 v181, v138, v139
	v_cvt_pk_bf16_f32 v182, v140, v141
	v_cvt_pk_bf16_f32 v183, v142, v143
	global_store_dwordx2 v191, v[176:177], s[8:9]
	global_store_dwordx2 v191, v[178:179], s[8:9] offset:512
	global_store_dwordx2 v191, v[180:181], s[8:9] offset:1024
	global_store_dwordx2 v191, v[182:183], s[8:9] offset:1536
	s_add_u32 s8, s8, s12
	s_addc_u32 s9, s9, 0
	s_branch .Lpnorm_done
.Lpnorm_drain2:
	s_waitcnt vmcnt(4)
	v_pk_mul_f32 v[184:185], v[128:129], v[128:129]
	v_pk_mul_f32 v[176:177], v[130:131], v[130:131]
	v_pk_fma_f32 v[184:185], v[132:133], v[132:133], v[184:185]
	v_pk_fma_f32 v[176:177], v[134:135], v[134:135], v[176:177]
	v_pk_fma_f32 v[184:185], v[136:137], v[136:137], v[184:185]
	v_pk_fma_f32 v[176:177], v[138:139], v[138:139], v[176:177]
	v_pk_fma_f32 v[184:185], v[140:141], v[140:141], v[184:185]
	v_pk_fma_f32 v[176:177], v[142:143], v[142:143], v[176:177]
	v_pk_add_f32 v[184:185], v[184:185], v[176:177]
	s_nop 0
	v_add_f32_e32 v184, v184, v185
	s_nop 1
	v_add_f32_dpp v184, v184, v184 quad_perm:[1,0,3,2] row_mask:0xf bank_mask:0xf
	s_nop 1
	v_add_f32_dpp v184, v184, v184 quad_perm:[2,3,0,1] row_mask:0xf bank_mask:0xf
	s_nop 1
	v_add_f32_dpp v184, v184, v184 row_half_mirror row_mask:0xf bank_mask:0xf
	s_nop 1
	v_add_f32_dpp v184, v184, v184 row_mirror row_mask:0xf bank_mask:0xf
	s_nop 1
	v_add_f32_dpp v184, v184, v184 row_bcast:15 row_mask:0xa bank_mask:0xf
	s_nop 1
	v_add_f32_dpp v184, v184, v184 row_bcast:31 row_mask:0xc bank_mask:0xf
	s_nop 1
	v_readlane_b32 s13, v184, 63
	s_nop 3
	v_fma_f32 v186, s13, v188, v189
	v_rsq_f32_e32 v186, v186
	s_nop 0
	v_mov_b32_e32 v187, v186
	v_pk_mul_f32 v[128:129], v[128:129], v[186:187]
	v_pk_mul_f32 v[130:131], v[130:131], v[186:187]
	v_pk_mul_f32 v[132:133], v[132:133], v[186:187]
	v_pk_mul_f32 v[134:135], v[134:135], v[186:187]
	v_pk_mul_f32 v[136:137], v[136:137], v[186:187]
	v_pk_mul_f32 v[138:139], v[138:139], v[186:187]
	v_pk_mul_f32 v[140:141], v[140:141], v[186:187]
	v_pk_mul_f32 v[142:143], v[142:143], v[186:187]
	v_pk_mul_f32 v[128:129], v[128:129], v[160:161]
	v_pk_mul_f32 v[130:131], v[130:131], v[162:163]
	v_pk_mul_f32 v[132:133], v[132:133], v[164:165]
	v_pk_mul_f32 v[134:135], v[134:135], v[166:167]
	v_pk_mul_f32 v[136:137], v[136:137], v[168:169]
	v_pk_mul_f32 v[138:139], v[138:139], v[170:171]
	v_pk_mul_f32 v[140:141], v[140:141], v[172:173]
	v_pk_mul_f32 v[142:143], v[142:143], v[174:175]
	v_cvt_pk_bf16_f32 v176, v128, v129
	v_cvt_pk_bf16_f32 v177, v130, v131
	v_cvt_pk_bf16_f32 v178, v132, v133
	v_cvt_pk_bf16_f32 v179, v134, v135
	v_cvt_pk_bf16_f32 v180, v136, v137
	v_cvt_pk_bf16_f32 v181, v138, v139
	v_cvt_pk_bf16_f32 v182, v140, v141
	v_cvt_pk_bf16_f32 v183, v142, v143
	global_store_dwordx2 v191, v[176:177], s[8:9]
	global_store_dwordx2 v191, v[178:179], s[8:9] offset:512
	global_store_dwordx2 v191, v[180:181], s[8:9] offset:1024
	global_store_dwordx2 v191, v[182:183], s[8:9] offset:1536
	s_add_u32 s8, s8, s12
	s_addc_u32 s9, s9, 0
	s_waitcnt vmcnt(4)
	v_pk_mul_f32 v[184:185], v[64:65], v[64:65]
	v_pk_mul_f32 v[176:177], v[66:67], v[66:67]
	v_pk_fma_f32 v[184:185], v[68:69], v[68:69], v[184:185]
	v_pk_fma_f32 v[176:177], v[70:71], v[70:71], v[176:177]
	v_pk_fma_f32 v[184:185], v[72:73], v[72:73], v[184:185]
	v_pk_fma_f32 v[176:177], v[74:75], v[74:75], v[176:177]
	v_pk_fma_f32 v[184:185], v[76:77], v[76:77], v[184:185]
	v_pk_fma_f32 v[176:177], v[78:79], v[78:79], v[176:177]
	v_pk_add_f32 v[184:185], v[184:185], v[176:177]
	s_nop 0
	v_add_f32_e32 v184, v184, v185
	s_nop 1
	v_add_f32_dpp v184, v184, v184 quad_perm:[1,0,3,2] row_mask:0xf bank_mask:0xf
	s_nop 1
	v_add_f32_dpp v184, v184, v184 quad_perm:[2,3,0,1] row_mask:0xf bank_mask:0xf
	s_nop 1
	v_add_f32_dpp v184, v184, v184 row_half_mirror row_mask:0xf bank_mask:0xf
	s_nop 1
	v_add_f32_dpp v184, v184, v184 row_mirror row_mask:0xf bank_mask:0xf
	s_nop 1
	v_add_f32_dpp v184, v184, v184 row_bcast:15 row_mask:0xa bank_mask:0xf
	s_nop 1
	v_add_f32_dpp v184, v184, v184 row_bcast:31 row_mask:0xc bank_mask:0xf
	s_nop 1
	v_readlane_b32 s13, v184, 63
	s_nop 3
	v_fma_f32 v186, s13, v188, v189
	v_rsq_f32_e32 v186, v186
	s_nop 0
	v_mov_b32_e32 v187, v186
	v_pk_mul_f32 v[64:65], v[64:65], v[186:187]
	v_pk_mul_f32 v[66:67], v[66:67], v[186:187]
	v_pk_mul_f32 v[68:69], v[68:69], v[186:187]
	v_pk_mul_f32 v[70:71], v[70:71], v[186:187]
	v_pk_mul_f32 v[72:73], v[72:73], v[186:187]
	v_pk_mul_f32 v[74:75], v[74:75], v[186:187]
	v_pk_mul_f32 v[76:77], v[76:77], v[186:187]
	v_pk_mul_f32 v[78:79], v[78:79], v[186:187]
	v_pk_mul_f32 v[64:65], v[64:65], v[160:161]
	v_pk_mul_f32 v[66:67], v[66:67], v[162:163]
	v_pk_mul_f32 v[68:69], v[68:69], v[164:165]
	v_pk_mul_f32 v[70:71], v[70:71], v[166:167]
	v_pk_mul_f32 v[72:73], v[72:73], v[168:169]
	v_pk_mul_f32 v[74:75], v[74:75], v[170:171]
	v_pk_mul_f32 v[76:77], v[76:77], v[172:173]
	v_pk_mul_f32 v[78:79], v[78:79], v[174:175]
	v_cvt_pk_bf16_f32 v176, v64, v65
	v_cvt_pk_bf16_f32 v177, v66, v67
	v_cvt_pk_bf16_f32 v178, v68, v69
	v_cvt_pk_bf16_f32 v179, v70, v71
	v_cvt_pk_bf16_f32 v180, v72, v73
	v_cvt_pk_bf16_f32 v181, v74, v75
	v_cvt_pk_bf16_f32 v182, v76, v77
	v_cvt_pk_bf16_f32 v183, v78, v79
	global_store_dwordx2 v191, v[176:177], s[8:9]
	global_store_dwordx2 v191, v[178:179], s[8:9] offset:512
	global_store_dwordx2 v191, v[180:181], s[8:9] offset:1024
	global_store_dwordx2 v191, v[182:183], s[8:9] offset:1536
	s_add_u32 s8, s8, s12
	s_addc_u32 s9, s9, 0
.Lpnorm_done:
.LBB0_111:
	s_or_b64 exec, exec, s[4:5]
	v_cmp_gt_i32_e32 vcc, 16, v38
	s_and_saveexec_b64 s[0:1], vcc
	s_cbranch_execz .LBB0_114
	v_mbcnt_lo_u32_b32 v1, -1, 0
	v_mbcnt_hi_u32_b32 v2, -1, v1
	v_and_b32_e32 v1, 64, v2
	v_add_u32_e32 v3, 64, v1
	v_xor_b32_e32 v1, 32, v2
	v_cmp_lt_i32_e32 vcc, v1, v3
	v_xor_b32_e32 v4, 16, v2
	v_ashrrev_i32_e32 v39, 31, v38
	v_cndmask_b32_e32 v1, v2, v1, vcc
	v_cmp_lt_i32_e32 vcc, v4, v3
	v_lshlrev_b64 v[6:7], 12, v[38:39]
	v_or_b32_e32 v6, v6, v40
	v_cndmask_b32_e32 v4, v2, v4, vcc
	v_lshlrev_b32_e32 v8, 2, v4
	v_xor_b32_e32 v4, 8, v2
	v_cmp_lt_i32_e32 vcc, v4, v3
	v_mov_b32_e32 v41, 0
	s_mov_b64 s[2:3], 0x19fe0800
	v_cndmask_b32_e32 v4, v2, v4, vcc
	v_lshlrev_b32_e32 v9, 2, v4
	v_xor_b32_e32 v4, 4, v2
	v_cmp_lt_i32_e32 vcc, v4, v3
	s_ashr_i32 s7, s6, 31
	v_lshl_add_u64 v[6:7], s[38:39], 0, v[6:7]
	v_cndmask_b32_e32 v4, v2, v4, vcc
	v_lshlrev_b32_e32 v10, 2, v4
	v_xor_b32_e32 v4, 2, v2
	v_cmp_lt_i32_e32 vcc, v4, v3
	s_mov_b64 s[4:5], 0xc00
	v_lshlrev_b32_e32 v1, 2, v1
	v_cndmask_b32_e32 v4, v2, v4, vcc
	v_lshlrev_b32_e32 v11, 2, v4
	v_xor_b32_e32 v4, 1, v2
	v_cmp_lt_i32_e32 vcc, v4, v3
	v_lshl_add_u64 v[6:7], v[6:7], 0, s[4:5]
	s_lshl_b64 s[4:5], s[6:7], 12
	v_cndmask_b32_e32 v2, v2, v4, vcc
	v_lshlrev_b64 v[4:5], 11, v[38:39]
	v_lshl_or_b32 v4, v45, 3, v4
	v_lshl_add_u64 v[4:5], s[20:21], 0, v[4:5]
	v_lshlrev_b32_e32 v12, 2, v2
	v_lshl_add_u64 v[2:3], s[40:41], 0, v[40:41]
	v_lshl_add_u64 v[4:5], v[4:5], 0, s[2:3]
	s_lshl_b64 s[2:3], s[6:7], 11
	s_mov_b64 s[8:9], 0
	v_mov_b32_e32 v13, 0x358637bd
	s_mov_b32 s7, 0x800000

.LBB0_1040:
	s_cmp_lt_i32 s22, 6
	s_cselect_b64 s[0:1], -1, 0
	s_cmp_gt_i32 s23, 5
	s_cselect_b64 s[2:3], -1, 0
	s_and_b64 s[0:1], s[0:1], s[2:3]
	s_andn2_b64 vcc, exec, s[0:1]
	s_cbranch_vccnz .LBB0_1125
	v_and_b32_e32 v1, 63, v208
	v_lshl_add_u32 v18, s96, 3, v209
	s_mov_b32 s5, 0x8000
	s_lshl_b32 s4, s82, 3
	v_cmp_gt_i32_e32 vcc, s5, v18
	v_lshlrev_b32_e32 v20, 4, v1
	s_and_saveexec_b64 s[6:7], vcc
	s_cbranch_execz .LBB0_1054
	s_waitcnt vmcnt(0) lgkmcnt(0)
	v_readfirstlane_b32 s16, v209
	s_lshl_b32 s14, s96, 3
	s_add_u32 s14, s14, s16
	s_lshl_b32 s15, s82, 3
	s_cmp_ge_u32 s14, 0x8000
	s_cbranch_scc1 .LBB0_1054
	v_and_b32_e32 v174, 63, v208
	v_lshlrev_b32_e32 v175, 3, v174
	v_lshlrev_b32_e32 v174, 4, v174
	s_add_u32 s24, s40, 0x1000
	s_addc_u32 s25, s41, 0
	global_load_dwordx4 v[144:147], v174, s[24:25] offset:0
	global_load_dwordx4 v[148:151], v174, s[24:25] offset:1024
	global_load_dwordx4 v[152:155], v174, s[24:25] offset:2048
	global_load_dwordx4 v[156:159], v174, s[24:25] offset:3072
	v_mov_b32_e32 v172, 0x3a800000
	v_mov_b32_e32 v173, 0x358637bd
	s_lshl_b32 s16, s14, 12
	s_add_u32 s0, s36, s16
	s_addc_u32 s1, s37, 0
	s_lshl_b32 s16, s14, 11
	s_add_u32 s8, s20, s16
	s_addc_u32 s9, s21, 0
	s_add_u32 s8, s8, 0xf60000
	s_addc_u32 s9, s9, 0
	s_add_u32 s2, s20, s16
	s_addc_u32 s3, s21, 0
	s_add_u32 s2, s2, 0x15f60000
	s_addc_u32 s3, s3, 0
	s_lshl_b32 s10, s15, 12
	s_lshl_b32 s12, s15, 11
	global_load_dwordx4 v[48:51], v174, s[0:1] nt
	global_load_dwordx4 v[52:55], v174, s[0:1] offset:1024 nt
	global_load_dwordx4 v[56:59], v174, s[0:1] offset:2048 nt
	global_load_dwordx4 v[60:63], v174, s[0:1] offset:3072 nt
	global_load_dwordx2 v[64:65], v175, s[2:3]
	global_load_dwordx2 v[66:67], v175, s[2:3] offset:512
	global_load_dwordx2 v[68:69], v175, s[2:3] offset:1024
	global_load_dwordx2 v[70:71], v175, s[2:3] offset:1536
	s_add_u32 s0, s0, s10
	s_addc_u32 s1, s1, 0
	s_add_u32 s2, s2, s12
	s_addc_u32 s3, s3, 0
	s_add_u32 s14, s14, s15
	s_cmp_ge_u32 s14, 0x8000
	s_cbranch_scc0 .Lmnorm_two
	s_waitcnt vmcnt(0)
	v_lshlrev_b32_e32 v160, 16, v64
	v_and_b32_e32 v161, 0xffff0000, v64
	v_lshlrev_b32_e32 v162, 16, v65
	v_and_b32_e32 v163, 0xffff0000, v65
	v_pk_add_f32 v[48:49], v[48:49], v[160:161]
	v_pk_add_f32 v[50:51], v[50:51], v[162:163]
	v_lshlrev_b32_e32 v164, 16, v66
	v_and_b32_e32 v165, 0xffff0000, v66
	v_lshlrev_b32_e32 v166, 16, v67
	v_and_b32_e32 v167, 0xffff0000, v67
	v_pk_add_f32 v[52:53], v[52:53], v[164:165]
	v_pk_add_f32 v[54:55], v[54:55], v[166:167]
	v_lshlrev_b32_e32 v160, 16, v68
	v_and_b32_e32 v161, 0xffff0000, v68
	v_lshlrev_b32_e32 v162, 16, v69
	v_and_b32_e32 v163, 0xffff0000, v69
	v_pk_add_f32 v[56:57], v[56:57], v[160:161]
	v_pk_add_f32 v[58:59], v[58:59], v[162:163]
	v_lshlrev_b32_e32 v164, 16, v70
	v_and_b32_e32 v165, 0xffff0000, v70
	v_lshlrev_b32_e32 v166, 16, v71
	v_and_b32_e32 v167, 0xffff0000, v71
	v_pk_add_f32 v[60:61], v[60:61], v[164:165]
	v_pk_add_f32 v[62:63], v[62:63], v[166:167]
	v_pk_mul_f32 v[168:169], v[48:49], v[48:49]
	v_pk_mul_f32 v[160:161], v[50:51], v[50:51]
	v_pk_fma_f32 v[168:169], v[52:53], v[52:53], v[168:169]
	v_pk_fma_f32 v[160:161], v[54:55], v[54:55], v[160:161]
	v_pk_fma_f32 v[168:169], v[56:57], v[56:57], v[168:169]
	v_pk_fma_f32 v[160:161], v[58:59], v[58:59], v[160:161]
	v_pk_fma_f32 v[168:169], v[60:61], v[60:61], v[168:169]
	v_pk_fma_f32 v[160:161], v[62:63], v[62:63], v[160:161]
	v_pk_add_f32 v[168:169], v[168:169], v[160:161]
	s_nop 0
	v_add_f32_e32 v168, v168, v169
	s_nop 1
	v_add_f32_dpp v168, v168, v168 quad_perm:[1,0,3,2] row_mask:0xf bank_mask:0xf
	s_nop 1
	v_add_f32_dpp v168, v168, v168 quad_perm:[2,3,0,1] row_mask:0xf bank_mask:0xf
	s_nop 1
	v_add_f32_dpp v168, v168, v168 row_half_mirror row_mask:0xf bank_mask:0xf
	s_nop 1
	v_add_f32_dpp v168, v168, v168 row_mirror row_mask:0xf bank_mask:0xf
	s_nop 1
	v_add_f32_dpp v168, v168, v168 row_bcast:15 row_mask:0xa bank_mask:0xf
	s_nop 1
	v_add_f32_dpp v168, v168, v168 row_bcast:31 row_mask:0xc bank_mask:0xf
	s_nop 1
	v_readlane_b32 s16, v168, 63
	s_nop 3
	v_fma_f32 v170, s16, v172, v173
	v_rsq_f32_e32 v170, v170
	s_nop 0
	v_mov_b32_e32 v171, v170
	v_pk_mul_f32 v[48:49], v[48:49], v[170:171]
	v_pk_mul_f32 v[50:51], v[50:51], v[170:171]
	v_pk_mul_f32 v[52:53], v[52:53], v[170:171]
	v_pk_mul_f32 v[54:55], v[54:55], v[170:171]
	v_pk_mul_f32 v[56:57], v[56:57], v[170:171]
	v_pk_mul_f32 v[58:59], v[58:59], v[170:171]
	v_pk_mul_f32 v[60:61], v[60:61], v[170:171]
	v_pk_mul_f32 v[62:63], v[62:63], v[170:171]
	v_pk_mul_f32 v[48:49], v[48:49], v[144:145]
	v_pk_mul_f32 v[50:51], v[50:51], v[146:147]
	v_pk_mul_f32 v[52:53], v[52:53], v[148:149]
	v_pk_mul_f32 v[54:55], v[54:55], v[150:151]
	v_pk_mul_f32 v[56:57], v[56:57], v[152:153]
	v_pk_mul_f32 v[58:59], v[58:59], v[154:155]
	v_pk_mul_f32 v[60:61], v[60:61], v[156:157]
	v_pk_mul_f32 v[62:63], v[62:63], v[158:159]
	v_cvt_pk_bf16_f32 v160, v48, v49
	v_cvt_pk_bf16_f32 v161, v50, v51
	v_cvt_pk_bf16_f32 v162, v52, v53
	v_cvt_pk_bf16_f32 v163, v54, v55
	v_cvt_pk_bf16_f32 v164, v56, v57
	v_cvt_pk_bf16_f32 v165, v58, v59
	v_cvt_pk_bf16_f32 v166, v60, v61
	v_cvt_pk_bf16_f32 v167, v62, v63
	global_store_dwordx2 v175, v[160:161], s[8:9]
	global_store_dwordx2 v175, v[162:163], s[8:9] offset:512
	global_store_dwordx2 v175, v[164:165], s[8:9] offset:1024
	global_store_dwordx2 v175, v[166:167], s[8:9] offset:1536
	s_add_u32 s8, s8, s12
	s_addc_u32 s9, s9, 0
	s_branch .Lmnorm_done
.Lmnorm_two:
	global_load_dwordx4 v[80:83], v174, s[0:1] nt
	global_load_dwordx4 v[84:87], v174, s[0:1] offset:1024 nt
	global_load_dwordx4 v[88:91], v174, s[0:1] offset:2048 nt
	global_load_dwordx4 v[92:95], v174, s[0:1] offset:3072 nt
	global_load_dwordx2 v[96:97], v175, s[2:3]
	global_load_dwordx2 v[98:99], v175, s[2:3] offset:512
	global_load_dwordx2 v[100:101], v175, s[2:3] offset:1024
	global_load_dwordx2 v[102:103], v175, s[2:3] offset:1536
	s_add_u32 s0, s0, s10
	s_addc_u32 s1, s1, 0
	s_add_u32 s2, s2, s12
	s_addc_u32 s3, s3, 0
	s_add_u32 s14, s14, s15
.Lmnorm_loop:
	s_cmp_ge_u32 s14, 0x8000
	s_cbranch_scc1 .Lmnorm_drain0
	global_load_dwordx4 v[112:115], v174, s[0:1] nt
	global_load_dwordx4 v[116:119], v174, s[0:1] offset:1024 nt
	global_load_dwordx4 v[120:123], v174, s[0:1] offset:2048 nt
	global_load_dwordx4 v[124:127], v174, s[0:1] offset:3072 nt
	global_load_dwordx2 v[128:129], v175, s[2:3]
	global_load_dwordx2 v[130:131], v175, s[2:3] offset:512
	global_load_dwordx2 v[132:133], v175, s[2:3] offset:1024
	global_load_dwordx2 v[134:135], v175, s[2:3] offset:1536
	s_add_u32 s0, s0, s10
	s_addc_u32 s1, s1, 0
	s_add_u32 s2, s2, s12
	s_addc_u32 s3, s3, 0
	s_add_u32 s14, s14, s15
	s_waitcnt vmcnt(16)
	v_lshlrev_b32_e32 v160, 16, v64
	v_and_b32_e32 v161, 0xffff0000, v64
	v_lshlrev_b32_e32 v162, 16, v65
	v_and_b32_e32 v163, 0xffff0000, v65
	v_pk_add_f32 v[48:49], v[48:49], v[160:161]
	v_pk_add_f32 v[50:51], v[50:51], v[162:163]
	v_lshlrev_b32_e32 v164, 16, v66
	v_and_b32_e32 v165, 0xffff0000, v66
	v_lshlrev_b32_e32 v166, 16, v67
	v_and_b32_e32 v167, 0xffff0000, v67
	v_pk_add_f32 v[52:53], v[52:53], v[164:165]
	v_pk_add_f32 v[54:55], v[54:55], v[166:167]
	v_lshlrev_b32_e32 v160, 16, v68
	v_and_b32_e32 v161, 0xffff0000, v68
	v_lshlrev_b32_e32 v162, 16, v69
	v_and_b32_e32 v163, 0xffff0000, v69
	v_pk_add_f32 v[56:57], v[56:57], v[160:161]
	v_pk_add_f32 v[58:59], v[58:59], v[162:163]
	v_lshlrev_b32_e32 v164, 16, v70
	v_and_b32_e32 v165, 0xffff0000, v70
	v_lshlrev_b32_e32 v166, 16, v71
	v_and_b32_e32 v167, 0xffff0000, v71
	v_pk_add_f32 v[60:61], v[60:61], v[164:165]
	v_pk_add_f32 v[62:63], v[62:63], v[166:167]
	v_pk_mul_f32 v[168:169], v[48:49], v[48:49]
	v_pk_mul_f32 v[160:161], v[50:51], v[50:51]
	v_pk_fma_f32 v[168:169], v[52:53], v[52:53], v[168:169]
	v_pk_fma_f32 v[160:161], v[54:55], v[54:55], v[160:161]
	v_pk_fma_f32 v[168:169], v[56:57], v[56:57], v[168:169]
	v_pk_fma_f32 v[160:161], v[58:59], v[58:59], v[160:161]
	v_pk_fma_f32 v[168:169], v[60:61], v[60:61], v[168:169]
	v_pk_fma_f32 v[160:161], v[62:63], v[62:63], v[160:161]
	v_pk_add_f32 v[168:169], v[168:169], v[160:161]
	s_nop 0
	v_add_f32_e32 v168, v168, v169
	s_nop 1
	v_add_f32_dpp v168, v168, v168 quad_perm:[1,0,3,2] row_mask:0xf bank_mask:0xf
	s_nop 1
	v_add_f32_dpp v168, v168, v168 quad_perm:[2,3,0,1] row_mask:0xf bank_mask:0xf
	s_nop 1
	v_add_f32_dpp v168, v168, v168 row_half_mirror row_mask:0xf bank_mask:0xf
	s_nop 1
	v_add_f32_dpp v168, v168, v168 row_mirror row_mask:0xf bank_mask:0xf
	s_nop 1
	v_add_f32_dpp v168, v168, v168 row_bcast:15 row_mask:0xa bank_mask:0xf
	s_nop 1
	v_add_f32_dpp v168, v168, v168 row_bcast:31 row_mask:0xc bank_mask:0xf
	s_nop 1
	v_readlane_b32 s16, v168, 63
	s_nop 3
	v_fma_f32 v170, s16, v172, v173
	v_rsq_f32_e32 v170, v170
	s_nop 0
	v_mov_b32_e32 v171, v170
	v_pk_mul_f32 v[48:49], v[48:49], v[170:171]
	v_pk_mul_f32 v[50:51], v[50:51], v[170:171]
	v_pk_mul_f32 v[52:53], v[52:53], v[170:171]
	v_pk_mul_f32 v[54:55], v[54:55], v[170:171]
	v_pk_mul_f32 v[56:57], v[56:57], v[170:171]
	v_pk_mul_f32 v[58:59], v[58:59], v[170:171]
	v_pk_mul_f32 v[60:61], v[60:61], v[170:171]
	v_pk_mul_f32 v[62:63], v[62:63], v[170:171]
	v_pk_mul_f32 v[48:49], v[48:49], v[144:145]
	v_pk_mul_f32 v[50:51], v[50:51], v[146:147]
	v_pk_mul_f32 v[52:53], v[52:53], v[148:149]
	v_pk_mul_f32 v[54:55], v[54:55], v[150:151]
	v_pk_mul_f32 v[56:57], v[56:57], v[152:153]
	v_pk_mul_f32 v[58:59], v[58:59], v[154:155]
	v_pk_mul_f32 v[60:61], v[60:61], v[156:157]
	v_pk_mul_f32 v[62:63], v[62:63], v[158:159]
	v_cvt_pk_bf16_f32 v160, v48, v49
	v_cvt_pk_bf16_f32 v161, v50, v51
	v_cvt_pk_bf16_f32 v162, v52, v53
	v_cvt_pk_bf16_f32 v163, v54, v55
	v_cvt_pk_bf16_f32 v164, v56, v57
	v_cvt_pk_bf16_f32 v165, v58, v59
	v_cvt_pk_bf16_f32 v166, v60, v61
	v_cvt_pk_bf16_f32 v167, v62, v63
	global_store_dwordx2 v175, v[160:161], s[8:9]
	global_store_dwordx2 v175, v[162:163], s[8:9] offset:512
	global_store_dwordx2 v175, v[164:165], s[8:9] offset:1024
	global_store_dwordx2 v175, v[166:167], s[8:9] offset:1536
	s_add_u32 s8, s8, s12
	s_addc_u32 s9, s9, 0
	s_cmp_ge_u32 s14, 0x8000
	s_cbranch_scc1 .Lmnorm_drain1
	global_load_dwordx4 v[48:51], v174, s[0:1] nt
	global_load_dwordx4 v[52:55], v174, s[0:1] offset:1024 nt
	global_load_dwordx4 v[56:59], v174, s[0:1] offset:2048 nt
	global_load_dwordx4 v[60:63], v174, s[0:1] offset:3072 nt
	global_load_dwordx2 v[64:65], v175, s[2:3]
	global_load_dwordx2 v[66:67], v175, s[2:3] offset:512
	global_load_dwordx2 v[68:69], v175, s[2:3] offset:1024
	global_load_dwordx2 v[70:71], v175, s[2:3] offset:1536
	s_add_u32 s0, s0, s10
	s_addc_u32 s1, s1, 0
	s_add_u32 s2, s2, s12
	s_addc_u32 s3, s3, 0
	s_add_u32 s14, s14, s15
	s_waitcnt vmcnt(16)
	v_lshlrev_b32_e32 v160, 16, v96
	v_and_b32_e32 v161, 0xffff0000, v96
	v_lshlrev_b32_e32 v162, 16, v97
	v_and_b32_e32 v163, 0xffff0000, v97
	v_pk_add_f32 v[80:81], v[80:81], v[160:161]
	v_pk_add_f32 v[82:83], v[82:83], v[162:163]
	v_lshlrev_b32_e32 v164, 16, v98
	v_and_b32_e32 v165, 0xffff0000, v98
	v_lshlrev_b32_e32 v166, 16, v99
	v_and_b32_e32 v167, 0xffff0000, v99
	v_pk_add_f32 v[84:85], v[84:85], v[164:165]
	v_pk_add_f32 v[86:87], v[86:87], v[166:167]
	v_lshlrev_b32_e32 v160, 16, v100
	v_and_b32_e32 v161, 0xffff0000, v100
	v_lshlrev_b32_e32 v162, 16, v101
	v_and_b32_e32 v163, 0xffff0000, v101
	v_pk_add_f32 v[88:89], v[88:89], v[160:161]
	v_pk_add_f32 v[90:91], v[90:91], v[162:163]
	v_lshlrev_b32_e32 v164, 16, v102
	v_and_b32_e32 v165, 0xffff0000, v102
	v_lshlrev_b32_e32 v166, 16, v103
	v_and_b32_e32 v167, 0xffff0000, v103
	v_pk_add_f32 v[92:93], v[92:93], v[164:165]
	v_pk_add_f32 v[94:95], v[94:95], v[166:167]
	v_pk_mul_f32 v[168:169], v[80:81], v[80:81]
	v_pk_mul_f32 v[160:161], v[82:83], v[82:83]
	v_pk_fma_f32 v[168:169], v[84:85], v[84:85], v[168:169]
	v_pk_fma_f32 v[160:161], v[86:87], v[86:87], v[160:161]
	v_pk_fma_f32 v[168:169], v[88:89], v[88:89], v[168:169]
	v_pk_fma_f32 v[160:161], v[90:91], v[90:91], v[160:161]
	v_pk_fma_f32 v[168:169], v[92:93], v[92:93], v[168:169]
	v_pk_fma_f32 v[160:161], v[94:95], v[94:95], v[160:161]
	v_pk_add_f32 v[168:169], v[168:169], v[160:161]
	s_nop 0
	v_add_f32_e32 v168, v168, v169
	s_nop 1
	v_add_f32_dpp v168, v168, v168 quad_perm:[1,0,3,2] row_mask:0xf bank_mask:0xf
	s_nop 1
	v_add_f32_dpp v168, v168, v168 quad_perm:[2,3,0,1] row_mask:0xf bank_mask:0xf
	s_nop 1
	v_add_f32_dpp v168, v168, v168 row_half_mirror row_mask:0xf bank_mask:0xf
	s_nop 1
	v_add_f32_dpp v168, v168, v168 row_mirror row_mask:0xf bank_mask:0xf
	s_nop 1
	v_add_f32_dpp v168, v168, v168 row_bcast:15 row_mask:0xa bank_mask:0xf
	s_nop 1
	v_add_f32_dpp v168, v168, v168 row_bcast:31 row_mask:0xc bank_mask:0xf
	s_nop 1
	v_readlane_b32 s16, v168, 63
	s_nop 3
	v_fma_f32 v170, s16, v172, v173
	v_rsq_f32_e32 v170, v170
	s_nop 0
	v_mov_b32_e32 v171, v170
	v_pk_mul_f32 v[80:81], v[80:81], v[170:171]
	v_pk_mul_f32 v[82:83], v[82:83], v[170:171]
	v_pk_mul_f32 v[84:85], v[84:85], v[170:171]
	v_pk_mul_f32 v[86:87], v[86:87], v[170:171]
	v_pk_mul_f32 v[88:89], v[88:89], v[170:171]
	v_pk_mul_f32 v[90:91], v[90:91], v[170:171]
	v_pk_mul_f32 v[92:93], v[92:93], v[170:171]
	v_pk_mul_f32 v[94:95], v[94:95], v[170:171]
	v_pk_mul_f32 v[80:81], v[80:81], v[144:145]
	v_pk_mul_f32 v[82:83], v[82:83], v[146:147]
	v_pk_mul_f32 v[84:85], v[84:85], v[148:149]
	v_pk_mul_f32 v[86:87], v[86:87], v[150:151]
	v_pk_mul_f32 v[88:89], v[88:89], v[152:153]
	v_pk_mul_f32 v[90:91], v[90:91], v[154:155]
	v_pk_mul_f32 v[92:93], v[92:93], v[156:157]
	v_pk_mul_f32 v[94:95], v[94:95], v[158:159]
	v_cvt_pk_bf16_f32 v160, v80, v81
	v_cvt_pk_bf16_f32 v161, v82, v83
	v_cvt_pk_bf16_f32 v162, v84, v85
	v_cvt_pk_bf16_f32 v163, v86, v87
	v_cvt_pk_bf16_f32 v164, v88, v89
	v_cvt_pk_bf16_f32 v165, v90, v91
	v_cvt_pk_bf16_f32 v166, v92, v93
	v_cvt_pk_bf16_f32 v167, v94, v95
	global_store_dwordx2 v175, v[160:161], s[8:9]
	global_store_dwordx2 v175, v[162:163], s[8:9] offset:512
	global_store_dwordx2 v175, v[164:165], s[8:9] offset:1024
	global_store_dwordx2 v175, v[166:167], s[8:9] offset:1536
	s_add_u32 s8, s8, s12
	s_addc_u32 s9, s9, 0
	s_cmp_ge_u32 s14, 0x8000
	s_cbranch_scc1 .Lmnorm_drain2
	global_load_dwordx4 v[80:83], v174, s[0:1] nt
	global_load_dwordx4 v[84:87], v174, s[0:1] offset:1024 nt
	global_load_dwordx4 v[88:91], v174, s[0:1] offset:2048 nt
	global_load_dwordx4 v[92:95], v174, s[0:1] offset:3072 nt
	global_load_dwordx2 v[96:97], v175, s[2:3]
	global_load_dwordx2 v[98:99], v175, s[2:3] offset:512
	global_load_dwordx2 v[100:101], v175, s[2:3] offset:1024
	global_load_dwordx2 v[102:103], v175, s[2:3] offset:1536
	s_add_u32 s0, s0, s10
	s_addc_u32 s1, s1, 0
	s_add_u32 s2, s2, s12
	s_addc_u32 s3, s3, 0
	s_add_u32 s14, s14, s15
	s_waitcnt vmcnt(16)
	v_lshlrev_b32_e32 v160, 16, v128
	v_and_b32_e32 v161, 0xffff0000, v128
	v_lshlrev_b32_e32 v162, 16, v129
	v_and_b32_e32 v163, 0xffff0000, v129
	v_pk_add_f32 v[112:113], v[112:113], v[160:161]
	v_pk_add_f32 v[114:115], v[114:115], v[162:163]
	v_lshlrev_b32_e32 v164, 16, v130
	v_and_b32_e32 v165, 0xffff0000, v130
	v_lshlrev_b32_e32 v166, 16, v131
	v_and_b32_e32 v167, 0xffff0000, v131
	v_pk_add_f32 v[116:117], v[116:117], v[164:165]
	v_pk_add_f32 v[118:119], v[118:119], v[166:167]
	v_lshlrev_b32_e32 v160, 16, v132
	v_and_b32_e32 v161, 0xffff0000, v132
	v_lshlrev_b32_e32 v162, 16, v133
	v_and_b32_e32 v163, 0xffff0000, v133
	v_pk_add_f32 v[120:121], v[120:121], v[160:161]
	v_pk_add_f32 v[122:123], v[122:123], v[162:163]
	v_lshlrev_b32_e32 v164, 16, v134
	v_and_b32_e32 v165, 0xffff0000, v134
	v_lshlrev_b32_e32 v166, 16, v135
	v_and_b32_e32 v167, 0xffff0000, v135
	v_pk_add_f32 v[124:125], v[124:125], v[164:165]
	v_pk_add_f32 v[126:127], v[126:127], v[166:167]
	v_pk_mul_f32 v[168:169], v[112:113], v[112:113]
	v_pk_mul_f32 v[160:161], v[114:115], v[114:115]
	v_pk_fma_f32 v[168:169], v[116:117], v[116:117], v[168:169]
	v_pk_fma_f32 v[160:161], v[118:119], v[118:119], v[160:161]
	v_pk_fma_f32 v[168:169], v[120:121], v[120:121], v[168:169]
	v_pk_fma_f32 v[160:161], v[122:123], v[122:123], v[160:161]
	v_pk_fma_f32 v[168:169], v[124:125], v[124:125], v[168:169]
	v_pk_fma_f32 v[160:161], v[126:127], v[126:127], v[160:161]
	v_pk_add_f32 v[168:169], v[168:169], v[160:161]
	s_nop 0
	v_add_f32_e32 v168, v168, v169
	s_nop 1
	v_add_f32_dpp v168, v168, v168 quad_perm:[1,0,3,2] row_mask:0xf bank_mask:0xf
	s_nop 1
	v_add_f32_dpp v168, v168, v168 quad_perm:[2,3,0,1] row_mask:0xf bank_mask:0xf
	s_nop 1
	v_add_f32_dpp v168, v168, v168 row_half_mirror row_mask:0xf bank_mask:0xf
	s_nop 1
	v_add_f32_dpp v168, v168, v168 row_mirror row_mask:0xf bank_mask:0xf
	s_nop 1
	v_add_f32_dpp v168, v168, v168 row_bcast:15 row_mask:0xa bank_mask:0xf
	s_nop 1
	v_add_f32_dpp v168, v168, v168 row_bcast:31 row_mask:0xc bank_mask:0xf
	s_nop 1
	v_readlane_b32 s16, v168, 63
	s_nop 3
	v_fma_f32 v170, s16, v172, v173
	v_rsq_f32_e32 v170, v170
	s_nop 0
	v_mov_b32_e32 v171, v170
	v_pk_mul_f32 v[112:113], v[112:113], v[170:171]
	v_pk_mul_f32 v[114:115], v[114:115], v[170:171]
	v_pk_mul_f32 v[116:117], v[116:117], v[170:171]
	v_pk_mul_f32 v[118:119], v[118:119], v[170:171]
	v_pk_mul_f32 v[120:121], v[120:121], v[170:171]
	v_pk_mul_f32 v[122:123], v[122:123], v[170:171]
	v_pk_mul_f32 v[124:125], v[124:125], v[170:171]
	v_pk_mul_f32 v[126:127], v[126:127], v[170:171]
	v_pk_mul_f32 v[112:113], v[112:113], v[144:145]
	v_pk_mul_f32 v[114:115], v[114:115], v[146:147]
	v_pk_mul_f32 v[116:117], v[116:117], v[148:149]
	v_pk_mul_f32 v[118:119], v[118:119], v[150:151]
	v_pk_mul_f32 v[120:121], v[120:121], v[152:153]
	v_pk_mul_f32 v[122:123], v[122:123], v[154:155]
	v_pk_mul_f32 v[124:125], v[124:125], v[156:157]
	v_pk_mul_f32 v[126:127], v[126:127], v[158:159]
	v_cvt_pk_bf16_f32 v160, v112, v113
	v_cvt_pk_bf16_f32 v161, v114, v115
	v_cvt_pk_bf16_f32 v162, v116, v117
	v_cvt_pk_bf16_f32 v163, v118, v119
	v_cvt_pk_bf16_f32 v164, v120, v121
	v_cvt_pk_bf16_f32 v165, v122, v123
	v_cvt_pk_bf16_f32 v166, v124, v125
	v_cvt_pk_bf16_f32 v167, v126, v127
	global_store_dwordx2 v175, v[160:161], s[8:9]
	global_store_dwordx2 v175, v[162:163], s[8:9] offset:512
	global_store_dwordx2 v175, v[164:165], s[8:9] offset:1024
	global_store_dwordx2 v175, v[166:167], s[8:9] offset:1536
	s_add_u32 s8, s8, s12
	s_addc_u32 s9, s9, 0
	s_branch .Lmnorm_loop
.Lmnorm_drain0:
	s_waitcnt vmcnt(8)
	v_lshlrev_b32_e32 v160, 16, v64
	v_and_b32_e32 v161, 0xffff0000, v64
	v_lshlrev_b32_e32 v162, 16, v65
	v_and_b32_e32 v163, 0xffff0000, v65
	v_pk_add_f32 v[48:49], v[48:49], v[160:161]
	v_pk_add_f32 v[50:51], v[50:51], v[162:163]
	v_lshlrev_b32_e32 v164, 16, v66
	v_and_b32_e32 v165, 0xffff0000, v66
	v_lshlrev_b32_e32 v166, 16, v67
	v_and_b32_e32 v167, 0xffff0000, v67
	v_pk_add_f32 v[52:53], v[52:53], v[164:165]
	v_pk_add_f32 v[54:55], v[54:55], v[166:167]
	v_lshlrev_b32_e32 v160, 16, v68
	v_and_b32_e32 v161, 0xffff0000, v68
	v_lshlrev_b32_e32 v162, 16, v69
	v_and_b32_e32 v163, 0xffff0000, v69
	v_pk_add_f32 v[56:57], v[56:57], v[160:161]
	v_pk_add_f32 v[58:59], v[58:59], v[162:163]
	v_lshlrev_b32_e32 v164, 16, v70
	v_and_b32_e32 v165, 0xffff0000, v70
	v_lshlrev_b32_e32 v166, 16, v71
	v_and_b32_e32 v167, 0xffff0000, v71
	v_pk_add_f32 v[60:61], v[60:61], v[164:165]
	v_pk_add_f32 v[62:63], v[62:63], v[166:167]
	v_pk_mul_f32 v[168:169], v[48:49], v[48:49]
	v_pk_mul_f32 v[160:161], v[50:51], v[50:51]
	v_pk_fma_f32 v[168:169], v[52:53], v[52:53], v[168:169]
	v_pk_fma_f32 v[160:161], v[54:55], v[54:55], v[160:161]
	v_pk_fma_f32 v[168:169], v[56:57], v[56:57], v[168:169]
	v_pk_fma_f32 v[160:161], v[58:59], v[58:59], v[160:161]
	v_pk_fma_f32 v[168:169], v[60:61], v[60:61], v[168:169]
	v_pk_fma_f32 v[160:161], v[62:63], v[62:63], v[160:161]
	v_pk_add_f32 v[168:169], v[168:169], v[160:161]
	s_nop 0
	v_add_f32_e32 v168, v168, v169
	s_nop 1
	v_add_f32_dpp v168, v168, v168 quad_perm:[1,0,3,2] row_mask:0xf bank_mask:0xf
	s_nop 1
	v_add_f32_dpp v168, v168, v168 quad_perm:[2,3,0,1] row_mask:0xf bank_mask:0xf
	s_nop 1
	v_add_f32_dpp v168, v168, v168 row_half_mirror row_mask:0xf bank_mask:0xf
	s_nop 1
	v_add_f32_dpp v168, v168, v168 row_mirror row_mask:0xf bank_mask:0xf
	s_nop 1
	v_add_f32_dpp v168, v168, v168 row_bcast:15 row_mask:0xa bank_mask:0xf
	s_nop 1
	v_add_f32_dpp v168, v168, v168 row_bcast:31 row_mask:0xc bank_mask:0xf
	s_nop 1
	v_readlane_b32 s16, v168, 63
	s_nop 3
	v_fma_f32 v170, s16, v172, v173
	v_rsq_f32_e32 v170, v170
	s_nop 0
	v_mov_b32_e32 v171, v170
	v_pk_mul_f32 v[48:49], v[48:49], v[170:171]
	v_pk_mul_f32 v[50:51], v[50:51], v[170:171]
	v_pk_mul_f32 v[52:53], v[52:53], v[170:171]
	v_pk_mul_f32 v[54:55], v[54:55], v[170:171]
	v_pk_mul_f32 v[56:57], v[56:57], v[170:171]
	v_pk_mul_f32 v[58:59], v[58:59], v[170:171]
	v_pk_mul_f32 v[60:61], v[60:61], v[170:171]
	v_pk_mul_f32 v[62:63], v[62:63], v[170:171]
	v_pk_mul_f32 v[48:49], v[48:49], v[144:145]
	v_pk_mul_f32 v[50:51], v[50:51], v[146:147]
	v_pk_mul_f32 v[52:53], v[52:53], v[148:149]
	v_pk_mul_f32 v[54:55], v[54:55], v[150:151]
	v_pk_mul_f32 v[56:57], v[56:57], v[152:153]
	v_pk_mul_f32 v[58:59], v[58:59], v[154:155]
	v_pk_mul_f32 v[60:61], v[60:61], v[156:157]
	v_pk_mul_f32 v[62:63], v[62:63], v[158:159]
	v_cvt_pk_bf16_f32 v160, v48, v49
	v_cvt_pk_bf16_f32 v161, v50, v51
	v_cvt_pk_bf16_f32 v162, v52, v53
	v_cvt_pk_bf16_f32 v163, v54, v55
	v_cvt_pk_bf16_f32 v164, v56, v57
	v_cvt_pk_bf16_f32 v165, v58, v59
	v_cvt_pk_bf16_f32 v166, v60, v61
	v_cvt_pk_bf16_f32 v167, v62, v63
	global_store_dwordx2 v175, v[160:161], s[8:9]
	global_store_dwordx2 v175, v[162:163], s[8:9] offset:512
	global_store_dwordx2 v175, v[164:165], s[8:9] offset:1024
	global_store_dwordx2 v175, v[166:167], s[8:9] offset:1536
	s_add_u32 s8, s8, s12
	s_addc_u32 s9, s9, 0
	s_waitcnt vmcnt(4)
	v_lshlrev_b32_e32 v160, 16, v96
	v_and_b32_e32 v161, 0xffff0000, v96
	v_lshlrev_b32_e32 v162, 16, v97
	v_and_b32_e32 v163, 0xffff0000, v97
	v_pk_add_f32 v[80:81], v[80:81], v[160:161]
	v_pk_add_f32 v[82:83], v[82:83], v[162:163]
	v_lshlrev_b32_e32 v164, 16, v98
	v_and_b32_e32 v165, 0xffff0000, v98
	v_lshlrev_b32_e32 v166, 16, v99
	v_and_b32_e32 v167, 0xffff0000, v99
	v_pk_add_f32 v[84:85], v[84:85], v[164:165]
	v_pk_add_f32 v[86:87], v[86:87], v[166:167]
	v_lshlrev_b32_e32 v160, 16, v100
	v_and_b32_e32 v161, 0xffff0000, v100
	v_lshlrev_b32_e32 v162, 16, v101
	v_and_b32_e32 v163, 0xffff0000, v101
	v_pk_add_f32 v[88:89], v[88:89], v[160:161]
	v_pk_add_f32 v[90:91], v[90:91], v[162:163]
	v_lshlrev_b32_e32 v164, 16, v102
	v_and_b32_e32 v165, 0xffff0000, v102
	v_lshlrev_b32_e32 v166, 16, v103
	v_and_b32_e32 v167, 0xffff0000, v103
	v_pk_add_f32 v[92:93], v[92:93], v[164:165]
	v_pk_add_f32 v[94:95], v[94:95], v[166:167]
	v_pk_mul_f32 v[168:169], v[80:81], v[80:81]
	v_pk_mul_f32 v[160:161], v[82:83], v[82:83]
	v_pk_fma_f32 v[168:169], v[84:85], v[84:85], v[168:169]
	v_pk_fma_f32 v[160:161], v[86:87], v[86:87], v[160:161]
	v_pk_fma_f32 v[168:169], v[88:89], v[88:89], v[168:169]
	v_pk_fma_f32 v[160:161], v[90:91], v[90:91], v[160:161]
	v_pk_fma_f32 v[168:169], v[92:93], v[92:93], v[168:169]
	v_pk_fma_f32 v[160:161], v[94:95], v[94:95], v[160:161]
	v_pk_add_f32 v[168:169], v[168:169], v[160:161]
	s_nop 0
	v_add_f32_e32 v168, v168, v169
	s_nop 1
	v_add_f32_dpp v168, v168, v168 quad_perm:[1,0,3,2] row_mask:0xf bank_mask:0xf
	s_nop 1
	v_add_f32_dpp v168, v168, v168 quad_perm:[2,3,0,1] row_mask:0xf bank_mask:0xf
	s_nop 1
	v_add_f32_dpp v168, v168, v168 row_half_mirror row_mask:0xf bank_mask:0xf
	s_nop 1
	v_add_f32_dpp v168, v168, v168 row_mirror row_mask:0xf bank_mask:0xf
	s_nop 1
	v_add_f32_dpp v168, v168, v168 row_bcast:15 row_mask:0xa bank_mask:0xf
	s_nop 1
	v_add_f32_dpp v168, v168, v168 row_bcast:31 row_mask:0xc bank_mask:0xf
	s_nop 1
	v_readlane_b32 s16, v168, 63
	s_nop 3
	v_fma_f32 v170, s16, v172, v173
	v_rsq_f32_e32 v170, v170
	s_nop 0
	v_mov_b32_e32 v171, v170
	v_pk_mul_f32 v[80:81], v[80:81], v[170:171]
	v_pk_mul_f32 v[82:83], v[82:83], v[170:171]
	v_pk_mul_f32 v[84:85], v[84:85], v[170:171]
	v_pk_mul_f32 v[86:87], v[86:87], v[170:171]
	v_pk_mul_f32 v[88:89], v[88:89], v[170:171]
	v_pk_mul_f32 v[90:91], v[90:91], v[170:171]
	v_pk_mul_f32 v[92:93], v[92:93], v[170:171]
	v_pk_mul_f32 v[94:95], v[94:95], v[170:171]
	v_pk_mul_f32 v[80:81], v[80:81], v[144:145]
	v_pk_mul_f32 v[82:83], v[82:83], v[146:147]
	v_pk_mul_f32 v[84:85], v[84:85], v[148:149]
	v_pk_mul_f32 v[86:87], v[86:87], v[150:151]
	v_pk_mul_f32 v[88:89], v[88:89], v[152:153]
	v_pk_mul_f32 v[90:91], v[90:91], v[154:155]
	v_pk_mul_f32 v[92:93], v[92:93], v[156:157]
	v_pk_mul_f32 v[94:95], v[94:95], v[158:159]
	v_cvt_pk_bf16_f32 v160, v80, v81
	v_cvt_pk_bf16_f32 v161, v82, v83
	v_cvt_pk_bf16_f32 v162, v84, v85
	v_cvt_pk_bf16_f32 v163, v86, v87
	v_cvt_pk_bf16_f32 v164, v88, v89
	v_cvt_pk_bf16_f32 v165, v90, v91
	v_cvt_pk_bf16_f32 v166, v92, v93
	v_cvt_pk_bf16_f32 v167, v94, v95
	global_store_dwordx2 v175, v[160:161], s[8:9]
	global_store_dwordx2 v175, v[162:163], s[8:9] offset:512
	global_store_dwordx2 v175, v[164:165], s[8:9] offset:1024
	global_store_dwordx2 v175, v[166:167], s[8:9] offset:1536
	s_add_u32 s8, s8, s12
	s_addc_u32 s9, s9, 0
	s_branch .Lmnorm_done
.Lmnorm_drain1:
	s_waitcnt vmcnt(8)
	v_lshlrev_b32_e32 v160, 16, v96
	v_and_b32_e32 v161, 0xffff0000, v96
	v_lshlrev_b32_e32 v162, 16, v97
	v_and_b32_e32 v163, 0xffff0000, v97
	v_pk_add_f32 v[80:81], v[80:81], v[160:161]
	v_pk_add_f32 v[82:83], v[82:83], v[162:163]
	v_lshlrev_b32_e32 v164, 16, v98
	v_and_b32_e32 v165, 0xffff0000, v98
	v_lshlrev_b32_e32 v166, 16, v99
	v_and_b32_e32 v167, 0xffff0000, v99
	v_pk_add_f32 v[84:85], v[84:85], v[164:165]
	v_pk_add_f32 v[86:87], v[86:87], v[166:167]
	v_lshlrev_b32_e32 v160, 16, v100
	v_and_b32_e32 v161, 0xffff0000, v100
	v_lshlrev_b32_e32 v162, 16, v101
	v_and_b32_e32 v163, 0xffff0000, v101
	v_pk_add_f32 v[88:89], v[88:89], v[160:161]
	v_pk_add_f32 v[90:91], v[90:91], v[162:163]
	v_lshlrev_b32_e32 v164, 16, v102
	v_and_b32_e32 v165, 0xffff0000, v102
	v_lshlrev_b32_e32 v166, 16, v103
	v_and_b32_e32 v167, 0xffff0000, v103
	v_pk_add_f32 v[92:93], v[92:93], v[164:165]
	v_pk_add_f32 v[94:95], v[94:95], v[166:167]
	v_pk_mul_f32 v[168:169], v[80:81], v[80:81]
	v_pk_mul_f32 v[160:161], v[82:83], v[82:83]
	v_pk_fma_f32 v[168:169], v[84:85], v[84:85], v[168:169]
	v_pk_fma_f32 v[160:161], v[86:87], v[86:87], v[160:161]
	v_pk_fma_f32 v[168:169], v[88:89], v[88:89], v[168:169]
	v_pk_fma_f32 v[160:161], v[90:91], v[90:91], v[160:161]
	v_pk_fma_f32 v[168:169], v[92:93], v[92:93], v[168:169]
	v_pk_fma_f32 v[160:161], v[94:95], v[94:95], v[160:161]
	v_pk_add_f32 v[168:169], v[168:169], v[160:161]
	s_nop 0
	v_add_f32_e32 v168, v168, v169
	s_nop 1
	v_add_f32_dpp v168, v168, v168 quad_perm:[1,0,3,2] row_mask:0xf bank_mask:0xf
	s_nop 1
	v_add_f32_dpp v168, v168, v168 quad_perm:[2,3,0,1] row_mask:0xf bank_mask:0xf
	s_nop 1
	v_add_f32_dpp v168, v168, v168 row_half_mirror row_mask:0xf bank_mask:0xf
	s_nop 1
	v_add_f32_dpp v168, v168, v168 row_mirror row_mask:0xf bank_mask:0xf
	s_nop 1
	v_add_f32_dpp v168, v168, v168 row_bcast:15 row_mask:0xa bank_mask:0xf
	s_nop 1
	v_add_f32_dpp v168, v168, v168 row_bcast:31 row_mask:0xc bank_mask:0xf
	s_nop 1
	v_readlane_b32 s16, v168, 63
	s_nop 3
	v_fma_f32 v170, s16, v172, v173
	v_rsq_f32_e32 v170, v170
	s_nop 0
	v_mov_b32_e32 v171, v170
	v_pk_mul_f32 v[80:81], v[80:81], v[170:171]
	v_pk_mul_f32 v[82:83], v[82:83], v[170:171]
	v_pk_mul_f32 v[84:85], v[84:85], v[170:171]
	v_pk_mul_f32 v[86:87], v[86:87], v[170:171]
	v_pk_mul_f32 v[88:89], v[88:89], v[170:171]
	v_pk_mul_f32 v[90:91], v[90:91], v[170:171]
	v_pk_mul_f32 v[92:93], v[92:93], v[170:171]
	v_pk_mul_f32 v[94:95], v[94:95], v[170:171]
	v_pk_mul_f32 v[80:81], v[80:81], v[144:145]
	v_pk_mul_f32 v[82:83], v[82:83], v[146:147]
	v_pk_mul_f32 v[84:85], v[84:85], v[148:149]
	v_pk_mul_f32 v[86:87], v[86:87], v[150:151]
	v_pk_mul_f32 v[88:89], v[88:89], v[152:153]
	v_pk_mul_f32 v[90:91], v[90:91], v[154:155]
	v_pk_mul_f32 v[92:93], v[92:93], v[156:157]
	v_pk_mul_f32 v[94:95], v[94:95], v[158:159]
	v_cvt_pk_bf16_f32 v160, v80, v81
	v_cvt_pk_bf16_f32 v161, v82, v83
	v_cvt_pk_bf16_f32 v162, v84, v85
	v_cvt_pk_bf16_f32 v163, v86, v87
	v_cvt_pk_bf16_f32 v164, v88, v89
	v_cvt_pk_bf16_f32 v165, v90, v91
	v_cvt_pk_bf16_f32 v166, v92, v93
	v_cvt_pk_bf16_f32 v167, v94, v95
	global_store_dwordx2 v175, v[160:161], s[8:9]
	global_store_dwordx2 v175, v[162:163], s[8:9] offset:512
	global_store_dwordx2 v175, v[164:165], s[8:9] offset:1024
	global_store_dwordx2 v175, v[166:167], s[8:9] offset:1536
	s_add_u32 s8, s8, s12
	s_addc_u32 s9, s9, 0
	s_waitcnt vmcnt(4)
	v_lshlrev_b32_e32 v160, 16, v128
	v_and_b32_e32 v161, 0xffff0000, v128
	v_lshlrev_b32_e32 v162, 16, v129
	v_and_b32_e32 v163, 0xffff0000, v129
	v_pk_add_f32 v[112:113], v[112:113], v[160:161]
	v_pk_add_f32 v[114:115], v[114:115], v[162:163]
	v_lshlrev_b32_e32 v164, 16, v130
	v_and_b32_e32 v165, 0xffff0000, v130
	v_lshlrev_b32_e32 v166, 16, v131
	v_and_b32_e32 v167, 0xffff0000, v131
	v_pk_add_f32 v[116:117], v[116:117], v[164:165]
	v_pk_add_f32 v[118:119], v[118:119], v[166:167]
	v_lshlrev_b32_e32 v160, 16, v132
	v_and_b32_e32 v161, 0xffff0000, v132
	v_lshlrev_b32_e32 v162, 16, v133
	v_and_b32_e32 v163, 0xffff0000, v133
	v_pk_add_f32 v[120:121], v[120:121], v[160:161]
	v_pk_add_f32 v[122:123], v[122:123], v[162:163]
	v_lshlrev_b32_e32 v164, 16, v134
	v_and_b32_e32 v165, 0xffff0000, v134
	v_lshlrev_b32_e32 v166, 16, v135
	v_and_b32_e32 v167, 0xffff0000, v135
	v_pk_add_f32 v[124:125], v[124:125], v[164:165]
	v_pk_add_f32 v[126:127], v[126:127], v[166:167]
	v_pk_mul_f32 v[168:169], v[112:113], v[112:113]
	v_pk_mul_f32 v[160:161], v[114:115], v[114:115]
	v_pk_fma_f32 v[168:169], v[116:117], v[116:117], v[168:169]
	v_pk_fma_f32 v[160:161], v[118:119], v[118:119], v[160:161]
	v_pk_fma_f32 v[168:169], v[120:121], v[120:121], v[168:169]
	v_pk_fma_f32 v[160:161], v[122:123], v[122:123], v[160:161]
	v_pk_fma_f32 v[168:169], v[124:125], v[124:125], v[168:169]
	v_pk_fma_f32 v[160:161], v[126:127], v[126:127], v[160:161]
	v_pk_add_f32 v[168:169], v[168:169], v[160:161]
	s_nop 0
	v_add_f32_e32 v168, v168, v169
	s_nop 1
	v_add_f32_dpp v168, v168, v168 quad_perm:[1,0,3,2] row_mask:0xf bank_mask:0xf
	s_nop 1
	v_add_f32_dpp v168, v168, v168 quad_perm:[2,3,0,1] row_mask:0xf bank_mask:0xf
	s_nop 1
	v_add_f32_dpp v168, v168, v168 row_half_mirror row_mask:0xf bank_mask:0xf
	s_nop 1
	v_add_f32_dpp v168, v168, v168 row_mirror row_mask:0xf bank_mask:0xf
	s_nop 1
	v_add_f32_dpp v168, v168, v168 row_bcast:15 row_mask:0xa bank_mask:0xf
	s_nop 1
	v_add_f32_dpp v168, v168, v168 row_bcast:31 row_mask:0xc bank_mask:0xf
	s_nop 1
	v_readlane_b32 s16, v168, 63
	s_nop 3
	v_fma_f32 v170, s16, v172, v173
	v_rsq_f32_e32 v170, v170
	s_nop 0
	v_mov_b32_e32 v171, v170
	v_pk_mul_f32 v[112:113], v[112:113], v[170:171]
	v_pk_mul_f32 v[114:115], v[114:115], v[170:171]
	v_pk_mul_f32 v[116:117], v[116:117], v[170:171]
	v_pk_mul_f32 v[118:119], v[118:119], v[170:171]
	v_pk_mul_f32 v[120:121], v[120:121], v[170:171]
	v_pk_mul_f32 v[122:123], v[122:123], v[170:171]
	v_pk_mul_f32 v[124:125], v[124:125], v[170:171]
	v_pk_mul_f32 v[126:127], v[126:127], v[170:171]
	v_pk_mul_f32 v[112:113], v[112:113], v[144:145]
	v_pk_mul_f32 v[114:115], v[114:115], v[146:147]
	v_pk_mul_f32 v[116:117], v[116:117], v[148:149]
	v_pk_mul_f32 v[118:119], v[118:119], v[150:151]
	v_pk_mul_f32 v[120:121], v[120:121], v[152:153]
	v_pk_mul_f32 v[122:123], v[122:123], v[154:155]
	v_pk_mul_f32 v[124:125], v[124:125], v[156:157]
	v_pk_mul_f32 v[126:127], v[126:127], v[158:159]
	v_cvt_pk_bf16_f32 v160, v112, v113
	v_cvt_pk_bf16_f32 v161, v114, v115
	v_cvt_pk_bf16_f32 v162, v116, v117
	v_cvt_pk_bf16_f32 v163, v118, v119
	v_cvt_pk_bf16_f32 v164, v120, v121
	v_cvt_pk_bf16_f32 v165, v122, v123
	v_cvt_pk_bf16_f32 v166, v124, v125
	v_cvt_pk_bf16_f32 v167, v126, v127
	global_store_dwordx2 v175, v[160:161], s[8:9]
	global_store_dwordx2 v175, v[162:163], s[8:9] offset:512
	global_store_dwordx2 v175, v[164:165], s[8:9] offset:1024
	global_store_dwordx2 v175, v[166:167], s[8:9] offset:1536
	s_add_u32 s8, s8, s12
	s_addc_u32 s9, s9, 0
	s_branch .Lmnorm_done
.Lmnorm_drain2:
	s_waitcnt vmcnt(8)
	v_lshlrev_b32_e32 v160, 16, v128
	v_and_b32_e32 v161, 0xffff0000, v128
	v_lshlrev_b32_e32 v162, 16, v129
	v_and_b32_e32 v163, 0xffff0000, v129
	v_pk_add_f32 v[112:113], v[112:113], v[160:161]
	v_pk_add_f32 v[114:115], v[114:115], v[162:163]
	v_lshlrev_b32_e32 v164, 16, v130
	v_and_b32_e32 v165, 0xffff0000, v130
	v_lshlrev_b32_e32 v166, 16, v131
	v_and_b32_e32 v167, 0xffff0000, v131
	v_pk_add_f32 v[116:117], v[116:117], v[164:165]
	v_pk_add_f32 v[118:119], v[118:119], v[166:167]
	v_lshlrev_b32_e32 v160, 16, v132
	v_and_b32_e32 v161, 0xffff0000, v132
	v_lshlrev_b32_e32 v162, 16, v133
	v_and_b32_e32 v163, 0xffff0000, v133
	v_pk_add_f32 v[120:121], v[120:121], v[160:161]
	v_pk_add_f32 v[122:123], v[122:123], v[162:163]
	v_lshlrev_b32_e32 v164, 16, v134
	v_and_b32_e32 v165, 0xffff0000, v134
	v_lshlrev_b32_e32 v166, 16, v135
	v_and_b32_e32 v167, 0xffff0000, v135
	v_pk_add_f32 v[124:125], v[124:125], v[164:165]
	v_pk_add_f32 v[126:127], v[126:127], v[166:167]
	v_pk_mul_f32 v[168:169], v[112:113], v[112:113]
	v_pk_mul_f32 v[160:161], v[114:115], v[114:115]
	v_pk_fma_f32 v[168:169], v[116:117], v[116:117], v[168:169]
	v_pk_fma_f32 v[160:161], v[118:119], v[118:119], v[160:161]
	v_pk_fma_f32 v[168:169], v[120:121], v[120:121], v[168:169]
	v_pk_fma_f32 v[160:161], v[122:123], v[122:123], v[160:161]
	v_pk_fma_f32 v[168:169], v[124:125], v[124:125], v[168:169]
	v_pk_fma_f32 v[160:161], v[126:127], v[126:127], v[160:161]
	v_pk_add_f32 v[168:169], v[168:169], v[160:161]
	s_nop 0
	v_add_f32_e32 v168, v168, v169
	s_nop 1
	v_add_f32_dpp v168, v168, v168 quad_perm:[1,0,3,2] row_mask:0xf bank_mask:0xf
	s_nop 1
	v_add_f32_dpp v168, v168, v168 quad_perm:[2,3,0,1] row_mask:0xf bank_mask:0xf
	s_nop 1
	v_add_f32_dpp v168, v168, v168 row_half_mirror row_mask:0xf bank_mask:0xf
	s_nop 1
	v_add_f32_dpp v168, v168, v168 row_mirror row_mask:0xf bank_mask:0xf
	s_nop 1
	v_add_f32_dpp v168, v168, v168 row_bcast:15 row_mask:0xa bank_mask:0xf
	s_nop 1
	v_add_f32_dpp v168, v168, v168 row_bcast:31 row_mask:0xc bank_mask:0xf
	s_nop 1
	v_readlane_b32 s16, v168, 63
	s_nop 3
	v_fma_f32 v170, s16, v172, v173
	v_rsq_f32_e32 v170, v170
	s_nop 0
	v_mov_b32_e32 v171, v170
	v_pk_mul_f32 v[112:113], v[112:113], v[170:171]
	v_pk_mul_f32 v[114:115], v[114:115], v[170:171]
	v_pk_mul_f32 v[116:117], v[116:117], v[170:171]
	v_pk_mul_f32 v[118:119], v[118:119], v[170:171]
	v_pk_mul_f32 v[120:121], v[120:121], v[170:171]
	v_pk_mul_f32 v[122:123], v[122:123], v[170:171]
	v_pk_mul_f32 v[124:125], v[124:125], v[170:171]
	v_pk_mul_f32 v[126:127], v[126:127], v[170:171]
	v_pk_mul_f32 v[112:113], v[112:113], v[144:145]
	v_pk_mul_f32 v[114:115], v[114:115], v[146:147]
	v_pk_mul_f32 v[116:117], v[116:117], v[148:149]
	v_pk_mul_f32 v[118:119], v[118:119], v[150:151]
	v_pk_mul_f32 v[120:121], v[120:121], v[152:153]
	v_pk_mul_f32 v[122:123], v[122:123], v[154:155]
	v_pk_mul_f32 v[124:125], v[124:125], v[156:157]
	v_pk_mul_f32 v[126:127], v[126:127], v[158:159]
	v_cvt_pk_bf16_f32 v160, v112, v113
	v_cvt_pk_bf16_f32 v161, v114, v115
	v_cvt_pk_bf16_f32 v162, v116, v117
	v_cvt_pk_bf16_f32 v163, v118, v119
	v_cvt_pk_bf16_f32 v164, v120, v121
	v_cvt_pk_bf16_f32 v165, v122, v123
	v_cvt_pk_bf16_f32 v166, v124, v125
	v_cvt_pk_bf16_f32 v167, v126, v127
	global_store_dwordx2 v175, v[160:161], s[8:9]
	global_store_dwordx2 v175, v[162:163], s[8:9] offset:512
	global_store_dwordx2 v175, v[164:165], s[8:9] offset:1024
	global_store_dwordx2 v175, v[166:167], s[8:9] offset:1536
	s_add_u32 s8, s8, s12
	s_addc_u32 s9, s9, 0
	s_waitcnt vmcnt(4)
	v_lshlrev_b32_e32 v160, 16, v64
	v_and_b32_e32 v161, 0xffff0000, v64
	v_lshlrev_b32_e32 v162, 16, v65
	v_and_b32_e32 v163, 0xffff0000, v65
	v_pk_add_f32 v[48:49], v[48:49], v[160:161]
	v_pk_add_f32 v[50:51], v[50:51], v[162:163]
	v_lshlrev_b32_e32 v164, 16, v66
	v_and_b32_e32 v165, 0xffff0000, v66
	v_lshlrev_b32_e32 v166, 16, v67
	v_and_b32_e32 v167, 0xffff0000, v67
	v_pk_add_f32 v[52:53], v[52:53], v[164:165]
	v_pk_add_f32 v[54:55], v[54:55], v[166:167]
	v_lshlrev_b32_e32 v160, 16, v68
	v_and_b32_e32 v161, 0xffff0000, v68
	v_lshlrev_b32_e32 v162, 16, v69
	v_and_b32_e32 v163, 0xffff0000, v69
	v_pk_add_f32 v[56:57], v[56:57], v[160:161]
	v_pk_add_f32 v[58:59], v[58:59], v[162:163]
	v_lshlrev_b32_e32 v164, 16, v70
	v_and_b32_e32 v165, 0xffff0000, v70
	v_lshlrev_b32_e32 v166, 16, v71
	v_and_b32_e32 v167, 0xffff0000, v71
	v_pk_add_f32 v[60:61], v[60:61], v[164:165]
	v_pk_add_f32 v[62:63], v[62:63], v[166:167]
	v_pk_mul_f32 v[168:169], v[48:49], v[48:49]
	v_pk_mul_f32 v[160:161], v[50:51], v[50:51]
	v_pk_fma_f32 v[168:169], v[52:53], v[52:53], v[168:169]
	v_pk_fma_f32 v[160:161], v[54:55], v[54:55], v[160:161]
	v_pk_fma_f32 v[168:169], v[56:57], v[56:57], v[168:169]
	v_pk_fma_f32 v[160:161], v[58:59], v[58:59], v[160:161]
	v_pk_fma_f32 v[168:169], v[60:61], v[60:61], v[168:169]
	v_pk_fma_f32 v[160:161], v[62:63], v[62:63], v[160:161]
	v_pk_add_f32 v[168:169], v[168:169], v[160:161]
	s_nop 0
	v_add_f32_e32 v168, v168, v169
	s_nop 1
	v_add_f32_dpp v168, v168, v168 quad_perm:[1,0,3,2] row_mask:0xf bank_mask:0xf
	s_nop 1
	v_add_f32_dpp v168, v168, v168 quad_perm:[2,3,0,1] row_mask:0xf bank_mask:0xf
	s_nop 1
	v_add_f32_dpp v168, v168, v168 row_half_mirror row_mask:0xf bank_mask:0xf
	s_nop 1
	v_add_f32_dpp v168, v168, v168 row_mirror row_mask:0xf bank_mask:0xf
	s_nop 1
	v_add_f32_dpp v168, v168, v168 row_bcast:15 row_mask:0xa bank_mask:0xf
	s_nop 1
	v_add_f32_dpp v168, v168, v168 row_bcast:31 row_mask:0xc bank_mask:0xf
	s_nop 1
	v_readlane_b32 s16, v168, 63
	s_nop 3
	v_fma_f32 v170, s16, v172, v173
	v_rsq_f32_e32 v170, v170
	s_nop 0
	v_mov_b32_e32 v171, v170
	v_pk_mul_f32 v[48:49], v[48:49], v[170:171]
	v_pk_mul_f32 v[50:51], v[50:51], v[170:171]
	v_pk_mul_f32 v[52:53], v[52:53], v[170:171]
	v_pk_mul_f32 v[54:55], v[54:55], v[170:171]
	v_pk_mul_f32 v[56:57], v[56:57], v[170:171]
	v_pk_mul_f32 v[58:59], v[58:59], v[170:171]
	v_pk_mul_f32 v[60:61], v[60:61], v[170:171]
	v_pk_mul_f32 v[62:63], v[62:63], v[170:171]
	v_pk_mul_f32 v[48:49], v[48:49], v[144:145]
	v_pk_mul_f32 v[50:51], v[50:51], v[146:147]
	v_pk_mul_f32 v[52:53], v[52:53], v[148:149]
	v_pk_mul_f32 v[54:55], v[54:55], v[150:151]
	v_pk_mul_f32 v[56:57], v[56:57], v[152:153]
	v_pk_mul_f32 v[58:59], v[58:59], v[154:155]
	v_pk_mul_f32 v[60:61], v[60:61], v[156:157]
	v_pk_mul_f32 v[62:63], v[62:63], v[158:159]
	v_cvt_pk_bf16_f32 v160, v48, v49
	v_cvt_pk_bf16_f32 v161, v50, v51
	v_cvt_pk_bf16_f32 v162, v52, v53
	v_cvt_pk_bf16_f32 v163, v54, v55
	v_cvt_pk_bf16_f32 v164, v56, v57
	v_cvt_pk_bf16_f32 v165, v58, v59
	v_cvt_pk_bf16_f32 v166, v60, v61
	v_cvt_pk_bf16_f32 v167, v62, v63
	global_store_dwordx2 v175, v[160:161], s[8:9]
	global_store_dwordx2 v175, v[162:163], s[8:9] offset:512
	global_store_dwordx2 v175, v[164:165], s[8:9] offset:1024
	global_store_dwordx2 v175, v[166:167], s[8:9] offset:1536
	s_add_u32 s8, s8, s12
	s_addc_u32 s9, s9, 0
.Lmnorm_done:
.LBB0_1054:
	s_or_b64 exec, exec, s[6:7]
	v_cmp_gt_i32_e32 vcc, 16, v18
	s_and_saveexec_b64 s[0:1], vcc
	s_cbranch_execz .LBB0_1057
	s_waitcnt vmcnt(0)
	v_mbcnt_lo_u32_b32 v2, -1, 0
	v_mbcnt_hi_u32_b32 v2, -1, v2
	v_and_b32_e32 v3, 64, v2
	v_add_u32_e32 v3, 64, v3
	v_xor_b32_e32 v4, 32, v2
	v_cmp_lt_i32_e32 vcc, v4, v3
	s_add_u32 s2, s40, 0x1000
	v_mov_b32_e32 v21, 0
	v_cndmask_b32_e32 v4, v2, v4, vcc
	v_lshlrev_b32_e32 v14, 2, v4
	v_xor_b32_e32 v4, 16, v2
	v_cmp_lt_i32_e32 vcc, v4, v3
	v_ashrrev_i32_e32 v19, 31, v18
	s_addc_u32 s3, s41, 0
	v_cndmask_b32_e32 v4, v2, v4, vcc
	v_lshlrev_b32_e32 v15, 2, v4
	v_xor_b32_e32 v4, 8, v2
	v_cmp_lt_i32_e32 vcc, v4, v3
	v_mov_b32_e32 v5, v21
	v_or_b32_e32 v6, 0x800, v20
	v_cndmask_b32_e32 v4, v2, v4, vcc
	v_lshlrev_b32_e32 v16, 2, v4
	v_xor_b32_e32 v4, 4, v2
	v_cmp_lt_i32_e32 vcc, v4, v3
	v_mov_b32_e32 v7, v21
	v_or_b32_e32 v8, 0xc00, v20
	v_cndmask_b32_e32 v4, v2, v4, vcc
	v_lshlrev_b32_e32 v17, 2, v4
	v_xor_b32_e32 v4, 2, v2
	v_cmp_lt_i32_e32 vcc, v4, v3
	v_mov_b32_e32 v9, v21
	v_lshlrev_b64 v[10:11], 12, v[18:19]
	v_cndmask_b32_e32 v4, v2, v4, vcc
	v_lshlrev_b32_e32 v22, 2, v4
	v_xor_b32_e32 v4, 1, v2
	v_cmp_lt_i32_e32 vcc, v4, v3
	s_ashr_i32 s5, s4, 31
	v_lshlrev_b64 v[12:13], 11, v[18:19]
	v_cndmask_b32_e32 v2, v2, v4, vcc
	v_or_b32_e32 v4, 0x400, v20
	v_lshlrev_b32_e32 v23, 2, v2
	v_lshl_add_u64 v[2:3], s[2:3], 0, v[20:21]
	v_lshl_add_u64 v[4:5], s[2:3], 0, v[4:5]
	v_lshl_add_u64 v[6:7], s[2:3], 0, v[6:7]
	v_lshl_add_u64 v[8:9], s[2:3], 0, v[8:9]
	v_or_b32_e32 v10, v10, v20
	s_lshl_b64 s[2:3], s[4:5], 12
	v_lshl_or_b32 v12, v1, 3, v12
	s_lshl_b64 s[6:7], s[4:5], 11
	s_mov_b64 s[8:9], 0
	v_mov_b32_e32 v1, 0x358637bd
	s_mov_b32 s5, 0x800000
	s_mov_b32 s10, 0x19fe0000
